# mix2: causal-mask index registers recomputed on the fly (frees 28 VGPRs), used to prefetch the final-pass output loads before the P*V section
# speedup vs baseline: 1.0839x; 1.0051x over previous
; #define LAS __attribute__((address_space(3)))
; __device__ __forceinline__ unsigned cvt_pk_bf16(float lo, float hi) { unsigned r; asm volatile("v_cvt_pk_bf16_f32 %0, %1, %2" : "=v"(r) : "v"(lo), "v"(hi)); return r; }
; #define MFMA16(a, b, c) __builtin_amdgcn_mfma_f32_16x16x32_bf16((a), (b), (c), 0, 0, 0)
; __device__ void mix_sweep(const Params& P, LAS unsigned char* lds, int tok0, int pos0, int seqlen, int hd, int dir, bool state_only, bool final_pass,
;                           f32x4 (&Cacc)[9], float& m_state, float& aseg_sum, float lgam) {
;     ...
;             for (int nt = 0; nt < 8; ++nt) { f32x4 a = (f32x4){0.f, 0.f, 0.f, 0.f}; bf16x8 kr[4];
; #pragma unroll
;                 for (int s = 0; s < 4; ++s) kr[s] = ROWFRAG(IMG_K, 16 * nt, s);
;                 __builtin_amdgcn_sched_barrier(0);
; #pragma unroll
;                 for (int s = 0; s < 4; ++s) a = MFMA16(kr[s], qf[s], a);
;                 const f32x4 ct = *(const LAS f32x4*)(vcol + 16 * nt + 4 * fg); float p[4];
; #pragma unroll
;                 for (int e = 0; e < 4; ++e) { const int j = 16 * nt + 4 * fg + e;
;                     const bool keep = dir ? (is_m ? (j >= irow) : (j > irow)) : (j <= irow);
;                     const float ex = __builtin_amdgcn_exp2f(rt + ct[e]); p[e] = keep ? a[e] * ex : 0.f; }
;                 u32x2 pv; pv.x = cvt_pk_bf16(p[0], p[1]); pv.y = cvt_pk_bf16(p[2], p[3]);
;                 { LAUNDER_X16 *(LAS u32x2*)(lds + IMG_Q + CWA(nt)) = pv; } __builtin_amdgcn_sched_barrier(0); }
.LBB0_107:
	s_setprio 0
	v_lshl_add_u32 v220, v188, 2, 0
	v_add_u32_e32 v124, 0x22400, v220
	v_add_u32_e32 v125, 0x22000, v220
	v_add_u32_e32 v132, 0, v174
	ds_read_b32 v158, v124
	ds_read_b32 v171, v125
	ds_read_b128 v[124:127], v132 offset:32768
	v_add_u32_e32 v133, 0, v175
	v_add_u32_e32 v134, 0, v176
	ds_read_b128 v[128:131], v133 offset:32768
	ds_read_b128 v[136:139], v134 offset:32768
	v_add_u32_e32 v135, 0, v177
	ds_read_b128 v[140:143], v135 offset:32768
	s_waitcnt lgkmcnt(3)
	v_mfma_f32_16x16x32_bf16 v[124:127], v[124:127], v[92:95], 0
	s_mov_b64 s[18:19], -1
	s_andn2_b64 vcc, exec, s[12:13]
	s_waitcnt lgkmcnt(2)
	v_mfma_f32_16x16x32_bf16 v[128:131], v[128:131], v[96:99], v[124:127]
	s_waitcnt lgkmcnt(1)
	v_mfma_f32_16x16x32_bf16 v[128:131], v[136:139], v[100:103], v[128:131]
	s_nop 1
	ds_read_b128 v[124:127], v190
	v_cndmask_b32_e64 v136, 0, 1, s[12:13]
	v_cmp_ne_u32_e64 s[48:49], 1, v136
	s_waitcnt lgkmcnt(1)
	v_mfma_f32_16x16x32_bf16 v[128:131], v[140:143], v[88:91], v[128:131]
	v_or_b32_e32 v136, 0, v189
	v_or_b32_e32 v137, 1, v189
	v_or_b32_e32 v138, 2, v189
	v_or_b32_e32 v139, 3, v189
	v_cmp_le_i32_e64 s[16:17], v136, v188
	v_cmp_le_i32_e64 s[18:19], v137, v188
	v_cmp_le_i32_e64 s[50:51], v138, v188
	v_cmp_le_i32_e64 s[54:55], v139, v188
	s_cbranch_vccnz .Lmk_done_0
	v_cndmask_b32_e64 v140, 1, 0, s[42:43]
	v_add_u32_e32 v140, v140, v188
	v_cmp_ge_i32_e64 s[16:17], v136, v140
	v_cmp_ge_i32_e64 s[18:19], v137, v140
	v_cmp_ge_i32_e64 s[50:51], v138, v140
	v_cmp_ge_i32_e64 s[54:55], v139, v140
.Lmk_done_0:
.LBB0_139:
	s_waitcnt lgkmcnt(0)
	v_add_f32_e32 v126, v171, v126
	v_add_f32_e32 v125, v171, v125
	v_add_f32_e32 v124, v171, v124
	v_exp_f32_e32 v126, v126
	v_exp_f32_e32 v125, v125
	v_exp_f32_e32 v124, v124
	v_add_f32_e32 v127, v171, v127
	v_exp_f32_e32 v127, v127
	v_mul_f32_e32 v126, v130, v126
	v_mul_f32_e32 v125, v129, v125
	v_mul_f32_e32 v124, v128, v124
	v_cndmask_b32_e64 v126, 0, v126, s[50:51]
	v_cndmask_b32_e64 v125, 0, v125, s[18:19]
	v_cndmask_b32_e64 v124, 0, v124, s[16:17]
	v_mul_f32_e32 v127, v131, v127
	v_cndmask_b32_e64 v127, 0, v127, s[54:55]
	v_cvt_pk_bf16_f32 v124, v124, v125
	v_cvt_pk_bf16_f32 v125, v126, v127
	v_mov_b32_e32 v126, v179
	s_nop 0
	v_add_u32_e32 v126, v191, v126
	ds_write_b64 v126, v[124:125]
	ds_read_b128 v[124:127], v132 offset:36864
	ds_read_b128 v[128:131], v133 offset:36864
	ds_read_b128 v[136:139], v134 offset:36864
	ds_read_b128 v[140:143], v135 offset:36864
	s_waitcnt lgkmcnt(3)
	v_mfma_f32_16x16x32_bf16 v[124:127], v[124:127], v[92:95], 0
	s_mov_b64 s[18:19], -1
	s_and_b64 vcc, exec, s[48:49]
	s_waitcnt lgkmcnt(2)
	v_mfma_f32_16x16x32_bf16 v[124:127], v[128:131], v[96:99], v[124:127]
	ds_read_b128 v[128:131], v190 offset:64
	s_waitcnt lgkmcnt(2)
	v_mfma_f32_16x16x32_bf16 v[124:127], v[136:139], v[100:103], v[124:127]
	s_waitcnt lgkmcnt(1)
	v_mfma_f32_16x16x32_bf16 v[124:127], v[140:143], v[88:91], v[124:127]
	v_or_b32_e32 v136, 16, v189
	v_or_b32_e32 v137, 17, v189
	v_or_b32_e32 v138, 18, v189
	v_or_b32_e32 v139, 19, v189
	v_cmp_le_i32_e64 s[16:17], v136, v188
	v_cmp_le_i32_e64 s[18:19], v137, v188
	v_cmp_le_i32_e64 s[50:51], v138, v188
	v_cmp_le_i32_e64 s[54:55], v139, v188
	s_cbranch_vccnz .Lmk_done_1
	v_cndmask_b32_e64 v140, 1, 0, s[42:43]
	v_add_u32_e32 v140, v140, v188
	v_cmp_ge_i32_e64 s[16:17], v136, v140
	v_cmp_ge_i32_e64 s[18:19], v137, v140
	v_cmp_ge_i32_e64 s[50:51], v138, v140
	v_cmp_ge_i32_e64 s[54:55], v139, v140
.Lmk_done_1:
.LBB0_171:
	s_waitcnt lgkmcnt(0)
	v_add_f32_e32 v129, v171, v129
	v_exp_f32_e32 v129, v129
	v_add_f32_e32 v130, v171, v130
	v_add_f32_e32 v128, v171, v128
	v_exp_f32_e32 v130, v130
	v_mul_f32_e32 v125, v125, v129
	v_exp_f32_e32 v128, v128
	v_add_f32_e32 v129, v171, v131
	v_exp_f32_e32 v129, v129
	v_mul_f32_e32 v126, v126, v130
	v_mul_f32_e32 v124, v124, v128
	v_cndmask_b32_e64 v126, 0, v126, s[50:51]
	v_cndmask_b32_e64 v125, 0, v125, s[18:19]
	v_cndmask_b32_e64 v124, 0, v124, s[16:17]
	v_mul_f32_e32 v127, v127, v129
	v_cndmask_b32_e64 v127, 0, v127, s[54:55]
	v_cvt_pk_bf16_f32 v124, v124, v125
	v_cvt_pk_bf16_f32 v125, v126, v127
	v_mov_b32_e32 v126, v179
	s_nop 0
	v_xad_u32 v126, v126, 32, v191
	ds_write_b64 v126, v[124:125]
	ds_read_b128 v[124:127], v132 offset:40960
	ds_read_b128 v[128:131], v133 offset:40960
	ds_read_b128 v[136:139], v134 offset:40960
	ds_read_b128 v[140:143], v135 offset:40960
	s_waitcnt lgkmcnt(3)
	v_mfma_f32_16x16x32_bf16 v[124:127], v[124:127], v[92:95], 0
	s_mov_b64 s[18:19], -1
	s_and_b64 vcc, exec, s[48:49]
	s_waitcnt lgkmcnt(2)
	v_mfma_f32_16x16x32_bf16 v[124:127], v[128:131], v[96:99], v[124:127]
	ds_read_b128 v[128:131], v190 offset:128
	s_waitcnt lgkmcnt(2)
	v_mfma_f32_16x16x32_bf16 v[124:127], v[136:139], v[100:103], v[124:127]
	s_waitcnt lgkmcnt(1)
	v_mfma_f32_16x16x32_bf16 v[124:127], v[140:143], v[88:91], v[124:127]
	v_or_b32_e32 v136, 32, v189
	v_or_b32_e32 v137, 33, v189
	v_or_b32_e32 v138, 34, v189
	v_or_b32_e32 v139, 35, v189
	v_cmp_le_i32_e64 s[16:17], v136, v188
	v_cmp_le_i32_e64 s[18:19], v137, v188
	v_cmp_le_i32_e64 s[50:51], v138, v188
	v_cmp_le_i32_e64 s[54:55], v139, v188
	s_cbranch_vccnz .Lmk_done_2
	v_cndmask_b32_e64 v140, 1, 0, s[42:43]
	v_add_u32_e32 v140, v140, v188
	v_cmp_ge_i32_e64 s[16:17], v136, v140
	v_cmp_ge_i32_e64 s[18:19], v137, v140
	v_cmp_ge_i32_e64 s[50:51], v138, v140
	v_cmp_ge_i32_e64 s[54:55], v139, v140
; #define LAS __attribute__((address_space(3)))
; __device__ __forceinline__ unsigned cvt_pk_bf16(float lo, float hi) { unsigned r; asm volatile("v_cvt_pk_bf16_f32 %0, %1, %2" : "=v"(r) : "v"(lo), "v"(hi)); return r; }
; #define MFMA16(a, b, c) __builtin_amdgcn_mfma_f32_16x16x32_bf16((a), (b), (c), 0, 0, 0)
; __device__ void mix_sweep(const Params& P, LAS unsigned char* lds, int tok0, int pos0, int seqlen, int hd, int dir, bool state_only, bool final_pass,
;                           f32x4 (&Cacc)[9], float& m_state, float& aseg_sum, float lgam) {
;     ...
;             for (int nt = 0; nt < 8; ++nt) { f32x4 a = (f32x4){0.f, 0.f, 0.f, 0.f}; bf16x8 kr[4];
; #pragma unroll
;                 for (int s = 0; s < 4; ++s) kr[s] = ROWFRAG(IMG_K, 16 * nt, s);
;                 __builtin_amdgcn_sched_barrier(0);
; #pragma unroll
;                 for (int s = 0; s < 4; ++s) a = MFMA16(kr[s], qf[s], a);
;                 const f32x4 ct = *(const LAS f32x4*)(vcol + 16 * nt + 4 * fg); float p[4];
; #pragma unroll
;                 for (int e = 0; e < 4; ++e) { const int j = 16 * nt + 4 * fg + e;
;                     const bool keep = dir ? (is_m ? (j >= irow) : (j > irow)) : (j <= irow);
;                     const float ex = __builtin_amdgcn_exp2f(rt + ct[e]); p[e] = keep ? a[e] * ex : 0.f; }
;                 u32x2 pv; pv.x = cvt_pk_bf16(p[0], p[1]); pv.y = cvt_pk_bf16(p[2], p[3]);
;                 { LAUNDER_X16 *(LAS u32x2*)(lds + IMG_Q + CWA(nt)) = pv; } __builtin_amdgcn_sched_barrier(0); }
.Lmk_done_2:
.LBB0_203:
	s_waitcnt lgkmcnt(0)
	v_add_f32_e32 v129, v171, v129
	v_exp_f32_e32 v129, v129
	v_add_f32_e32 v130, v171, v130
	v_add_f32_e32 v128, v171, v128
	v_exp_f32_e32 v130, v130
	v_mul_f32_e32 v125, v125, v129
	v_exp_f32_e32 v128, v128
	v_add_f32_e32 v129, v171, v131
	v_exp_f32_e32 v129, v129
	v_mul_f32_e32 v126, v126, v130
	v_mul_f32_e32 v124, v124, v128
	v_cndmask_b32_e64 v126, 0, v126, s[50:51]
	v_cndmask_b32_e64 v125, 0, v125, s[18:19]
	v_cndmask_b32_e64 v124, 0, v124, s[16:17]
	v_mul_f32_e32 v127, v127, v129
	v_cndmask_b32_e64 v127, 0, v127, s[54:55]
	v_cvt_pk_bf16_f32 v124, v124, v125
	v_cvt_pk_bf16_f32 v125, v126, v127
	v_mov_b32_e32 v126, v179
	s_nop 0
	v_xad_u32 v126, v126, 64, v191
	ds_write_b64 v126, v[124:125]
	ds_read_b128 v[124:127], v132 offset:45056
	ds_read_b128 v[128:131], v133 offset:45056
	ds_read_b128 v[136:139], v134 offset:45056
	ds_read_b128 v[140:143], v135 offset:45056
	s_waitcnt lgkmcnt(3)
	v_mfma_f32_16x16x32_bf16 v[124:127], v[124:127], v[92:95], 0
	s_mov_b64 s[18:19], -1
	s_and_b64 vcc, exec, s[48:49]
	s_waitcnt lgkmcnt(2)
	v_mfma_f32_16x16x32_bf16 v[124:127], v[128:131], v[96:99], v[124:127]
	ds_read_b128 v[128:131], v190 offset:192
	s_waitcnt lgkmcnt(2)
	v_mfma_f32_16x16x32_bf16 v[124:127], v[136:139], v[100:103], v[124:127]
	s_waitcnt lgkmcnt(1)
	v_mfma_f32_16x16x32_bf16 v[124:127], v[140:143], v[88:91], v[124:127]
	v_or_b32_e32 v136, 48, v189
	v_or_b32_e32 v137, 49, v189
	v_or_b32_e32 v138, 50, v189
	v_or_b32_e32 v139, 51, v189
	v_cmp_le_i32_e64 s[16:17], v136, v188
	v_cmp_le_i32_e64 s[18:19], v137, v188
	v_cmp_le_i32_e64 s[50:51], v138, v188
	v_cmp_le_i32_e64 s[54:55], v139, v188
	s_cbranch_vccnz .Lmk_done_3
	v_cndmask_b32_e64 v140, 1, 0, s[42:43]
	v_add_u32_e32 v140, v140, v188
	v_cmp_ge_i32_e64 s[16:17], v136, v140
	v_cmp_ge_i32_e64 s[18:19], v137, v140
	v_cmp_ge_i32_e64 s[50:51], v138, v140
	v_cmp_ge_i32_e64 s[54:55], v139, v140
.Lmk_done_3:
.LBB0_235:
	s_waitcnt lgkmcnt(0)
	v_add_f32_e32 v129, v171, v129
	v_exp_f32_e32 v129, v129
	v_add_f32_e32 v130, v171, v130
	v_add_f32_e32 v128, v171, v128
	v_exp_f32_e32 v130, v130
	v_mul_f32_e32 v125, v125, v129
	v_exp_f32_e32 v128, v128
	v_add_f32_e32 v129, v171, v131
	v_exp_f32_e32 v129, v129
	v_mul_f32_e32 v126, v126, v130
	v_mul_f32_e32 v124, v124, v128
	v_cndmask_b32_e64 v126, 0, v126, s[50:51]
	v_cndmask_b32_e64 v125, 0, v125, s[18:19]
	v_cndmask_b32_e64 v124, 0, v124, s[16:17]
	v_mul_f32_e32 v127, v127, v129
	v_cndmask_b32_e64 v127, 0, v127, s[54:55]
	v_cvt_pk_bf16_f32 v124, v124, v125
	v_cvt_pk_bf16_f32 v125, v126, v127
	v_mov_b32_e32 v126, v179
	s_nop 0
	v_xad_u32 v126, v126, s33, v191
	ds_write_b64 v126, v[124:125]
	ds_read_b128 v[124:127], v132 offset:49152
	ds_read_b128 v[128:131], v133 offset:49152
	ds_read_b128 v[136:139], v134 offset:49152
	ds_read_b128 v[140:143], v135 offset:49152
	s_waitcnt lgkmcnt(3)
	v_mfma_f32_16x16x32_bf16 v[124:127], v[124:127], v[92:95], 0
	s_mov_b64 s[18:19], -1
	s_and_b64 vcc, exec, s[48:49]
	s_waitcnt lgkmcnt(2)
	v_mfma_f32_16x16x32_bf16 v[124:127], v[128:131], v[96:99], v[124:127]
	ds_read_b128 v[128:131], v190 offset:256
	s_waitcnt lgkmcnt(2)
	v_mfma_f32_16x16x32_bf16 v[124:127], v[136:139], v[100:103], v[124:127]
	s_waitcnt lgkmcnt(1)
	v_mfma_f32_16x16x32_bf16 v[124:127], v[140:143], v[88:91], v[124:127]
	v_or_b32_e32 v136, 64, v189
	v_or_b32_e32 v137, 0x41, v189
	v_or_b32_e32 v138, 0x42, v189
	v_or_b32_e32 v139, 0x43, v189
	v_cmp_le_i32_e64 s[16:17], v136, v188
	v_cmp_le_i32_e64 s[18:19], v137, v188
	v_cmp_le_i32_e64 s[50:51], v138, v188
	v_cmp_le_i32_e64 s[54:55], v139, v188
	s_cbranch_vccnz .Lmk_done_4
	v_cndmask_b32_e64 v140, 1, 0, s[42:43]
	v_add_u32_e32 v140, v140, v188
	v_cmp_ge_i32_e64 s[16:17], v136, v140
	v_cmp_ge_i32_e64 s[18:19], v137, v140
	v_cmp_ge_i32_e64 s[50:51], v138, v140
	v_cmp_ge_i32_e64 s[54:55], v139, v140
.Lmk_done_4:
.LBB0_267:
	s_waitcnt lgkmcnt(0)
	v_add_f32_e32 v129, v171, v129
	v_exp_f32_e32 v129, v129
	v_add_f32_e32 v130, v171, v130
	v_add_f32_e32 v128, v171, v128
	v_exp_f32_e32 v130, v130
	v_mul_f32_e32 v125, v125, v129
	v_exp_f32_e32 v128, v128
	v_add_f32_e32 v129, v171, v131
	v_exp_f32_e32 v129, v129
	v_mul_f32_e32 v126, v126, v130
	v_mul_f32_e32 v124, v124, v128
	v_cndmask_b32_e64 v126, 0, v126, s[50:51]
	v_cndmask_b32_e64 v125, 0, v125, s[18:19]
	v_cndmask_b32_e64 v124, 0, v124, s[16:17]
	v_mul_f32_e32 v127, v127, v129
	v_cndmask_b32_e64 v127, 0, v127, s[54:55]
	v_cvt_pk_bf16_f32 v124, v124, v125
	v_cvt_pk_bf16_f32 v125, v126, v127
	v_mov_b32_e32 v126, v179
	s_nop 0
	v_xad_u32 v126, v126, s25, v191
	ds_write_b64 v126, v[124:125]
	ds_read_b128 v[124:127], v132 offset:53248
	ds_read_b128 v[128:131], v133 offset:53248
	ds_read_b128 v[136:139], v134 offset:53248
	ds_read_b128 v[140:143], v135 offset:53248
	s_waitcnt lgkmcnt(3)
	v_mfma_f32_16x16x32_bf16 v[124:127], v[124:127], v[92:95], 0
	s_mov_b64 s[18:19], -1
	s_and_b64 vcc, exec, s[48:49]
	s_waitcnt lgkmcnt(2)
	v_mfma_f32_16x16x32_bf16 v[124:127], v[128:131], v[96:99], v[124:127]
	ds_read_b128 v[128:131], v190 offset:320
	s_waitcnt lgkmcnt(2)
	v_mfma_f32_16x16x32_bf16 v[124:127], v[136:139], v[100:103], v[124:127]
	s_waitcnt lgkmcnt(1)
	v_mfma_f32_16x16x32_bf16 v[124:127], v[140:143], v[88:91], v[124:127]
	v_or_b32_e32 v136, 0x50, v189
	v_or_b32_e32 v137, 0x51, v189
	v_or_b32_e32 v138, 0x52, v189
	v_or_b32_e32 v139, 0x53, v189
	v_cmp_le_i32_e64 s[16:17], v136, v188
	v_cmp_le_i32_e64 s[18:19], v137, v188
	v_cmp_le_i32_e64 s[50:51], v138, v188
	v_cmp_le_i32_e64 s[54:55], v139, v188
	s_cbranch_vccnz .Lmk_done_5
	v_cndmask_b32_e64 v140, 1, 0, s[42:43]
	v_add_u32_e32 v140, v140, v188
	v_cmp_ge_i32_e64 s[16:17], v136, v140
	v_cmp_ge_i32_e64 s[18:19], v137, v140
	v_cmp_ge_i32_e64 s[50:51], v138, v140
	v_cmp_ge_i32_e64 s[54:55], v139, v140
; #define LAS __attribute__((address_space(3)))
; __device__ __forceinline__ unsigned cvt_pk_bf16(float lo, float hi) { unsigned r; asm volatile("v_cvt_pk_bf16_f32 %0, %1, %2" : "=v"(r) : "v"(lo), "v"(hi)); return r; }
; #define MFMA16(a, b, c) __builtin_amdgcn_mfma_f32_16x16x32_bf16((a), (b), (c), 0, 0, 0)
; __device__ void mix_sweep(const Params& P, LAS unsigned char* lds, int tok0, int pos0, int seqlen, int hd, int dir, bool state_only, bool final_pass,
;                           f32x4 (&Cacc)[9], float& m_state, float& aseg_sum, float lgam) {
;     ...
;             const float wi = vwi[irow], rt = vrow[irow];
; #pragma unroll
;             for (int nt = 0; nt < 9; ++nt) O[nt] = O[nt] * wi;
; #pragma unroll
;             for (int nt = 0; nt < 8; ++nt) { f32x4 a = (f32x4){0.f, 0.f, 0.f, 0.f}; bf16x8 kr[4];
; #pragma unroll
;                 for (int s = 0; s < 4; ++s) kr[s] = ROWFRAG(IMG_K, 16 * nt, s);
;                 __builtin_amdgcn_sched_barrier(0);
; #pragma unroll
;                 for (int s = 0; s < 4; ++s) a = MFMA16(kr[s], qf[s], a);
;                 const f32x4 ct = *(const LAS f32x4*)(vcol + 16 * nt + 4 * fg); float p[4];
; #pragma unroll
;                 for (int e = 0; e < 4; ++e) { const int j = 16 * nt + 4 * fg + e;
;                     const bool keep = dir ? (is_m ? (j >= irow) : (j > irow)) : (j <= irow);
;                     const float ex = __builtin_amdgcn_exp2f(rt + ct[e]); p[e] = keep ? a[e] * ex : 0.f; }
;                 u32x2 pv; pv.x = cvt_pk_bf16(p[0], p[1]); pv.y = cvt_pk_bf16(p[2], p[3]);
;                 { LAUNDER_X16 *(LAS u32x2*)(lds + IMG_Q + CWA(nt)) = pv; } __builtin_amdgcn_sched_barrier(0); }
;             bf16x8 pf[4];
; #pragma unroll
;             for (int s = 0; s < 4; ++s) pf[s] = ROWFRAG(IMG_Q, 16 * w, s);
;             bf16x8 kf[4], kraw[4];
; #pragma unroll
;             for (int ks = 0; ks < 4; ++ks) kraw[ks] = trfrag_(lds, IMG_K + 256u * (32u * ks) + ktb0, IMG_K + 256u * (32u * ks + 4u) + ktb1);
;             __builtin_amdgcn_sched_barrier(0);
; #pragma unroll
;             for (int ks = 0; ks < 4; ++ks) { const bf16x8 raw = kraw[ks];
;                 const f32x4 k0 = *(const LAS f32x4*)(vkw + 32 * ks + 8 * fg), k1 = *(const LAS f32x4*)(vkw + 32 * ks + 8 * fg + 4);
.Lmk_done_5:
.LBB0_299:
	s_waitcnt lgkmcnt(0)
	v_add_f32_e32 v129, v171, v129
	v_exp_f32_e32 v129, v129
	v_add_f32_e32 v130, v171, v130
	v_add_f32_e32 v128, v171, v128
	v_exp_f32_e32 v130, v130
	v_mul_f32_e32 v125, v125, v129
	v_exp_f32_e32 v128, v128
	v_add_f32_e32 v129, v171, v131
	v_exp_f32_e32 v129, v129
	v_mul_f32_e32 v126, v126, v130
	v_mul_f32_e32 v124, v124, v128
	v_cndmask_b32_e64 v126, 0, v126, s[50:51]
	v_cndmask_b32_e64 v125, 0, v125, s[18:19]
	v_cndmask_b32_e64 v124, 0, v124, s[16:17]
	v_mul_f32_e32 v127, v127, v129
	v_cndmask_b32_e64 v127, 0, v127, s[54:55]
	v_cvt_pk_bf16_f32 v124, v124, v125
	v_cvt_pk_bf16_f32 v125, v126, v127
	v_mov_b32_e32 v126, v179
	s_nop 0
	v_xad_u32 v126, v126, s31, v191
	ds_write_b64 v126, v[124:125]
	ds_read_b128 v[124:127], v132 offset:57344
	ds_read_b128 v[128:131], v133 offset:57344
	ds_read_b128 v[136:139], v134 offset:57344
	ds_read_b128 v[140:143], v135 offset:57344
	s_waitcnt lgkmcnt(3)
	v_mfma_f32_16x16x32_bf16 v[124:127], v[124:127], v[92:95], 0
	s_mov_b64 s[18:19], -1
	s_and_b64 vcc, exec, s[48:49]
	s_waitcnt lgkmcnt(2)
	v_mfma_f32_16x16x32_bf16 v[124:127], v[128:131], v[96:99], v[124:127]
	ds_read_b128 v[128:131], v190 offset:384
	s_waitcnt lgkmcnt(2)
	v_mfma_f32_16x16x32_bf16 v[124:127], v[136:139], v[100:103], v[124:127]
	s_waitcnt lgkmcnt(1)
	v_mfma_f32_16x16x32_bf16 v[124:127], v[140:143], v[88:91], v[124:127]
	v_or_b32_e32 v136, 0x60, v189
	v_or_b32_e32 v137, 0x61, v189
	v_or_b32_e32 v138, 0x62, v189
	v_or_b32_e32 v139, 0x63, v189
	v_cmp_le_i32_e64 s[16:17], v136, v188
	v_cmp_le_i32_e64 s[18:19], v137, v188
	v_cmp_le_i32_e64 s[50:51], v138, v188
	v_cmp_le_i32_e64 s[54:55], v139, v188
	s_cbranch_vccnz .Lmk_done_6
	v_cndmask_b32_e64 v140, 1, 0, s[42:43]
	v_add_u32_e32 v140, v140, v188
	v_cmp_ge_i32_e64 s[16:17], v136, v140
	v_cmp_ge_i32_e64 s[18:19], v137, v140
	v_cmp_ge_i32_e64 s[50:51], v138, v140
	v_cmp_ge_i32_e64 s[54:55], v139, v140
.Lmk_done_6:
.LBB0_331:
	s_waitcnt lgkmcnt(0)
	v_add_f32_e32 v129, v171, v129
	v_exp_f32_e32 v129, v129
	v_add_f32_e32 v130, v171, v130
	v_add_f32_e32 v128, v171, v128
	v_exp_f32_e32 v130, v130
	v_mul_f32_e32 v125, v125, v129
	v_exp_f32_e32 v128, v128
	v_add_f32_e32 v129, v171, v131
	v_exp_f32_e32 v129, v129
	v_mul_f32_e32 v126, v126, v130
	v_mul_f32_e32 v124, v124, v128
	v_cndmask_b32_e64 v126, 0, v126, s[50:51]
	v_cndmask_b32_e64 v125, 0, v125, s[18:19]
	v_cndmask_b32_e64 v124, 0, v124, s[16:17]
	v_mul_f32_e32 v127, v127, v129
	v_cndmask_b32_e64 v127, 0, v127, s[54:55]
	v_cvt_pk_bf16_f32 v124, v124, v125
	v_cvt_pk_bf16_f32 v125, v126, v127
	v_mov_b32_e32 v126, v179
	s_nop 0
	v_xad_u32 v126, v126, s27, v191
	ds_write_b64 v126, v[124:125]
	ds_read_b128 v[124:127], v132 offset:61440
	ds_read_b128 v[128:131], v133 offset:61440
	ds_read_b128 v[136:139], v134 offset:61440
	ds_read_b128 v[132:135], v135 offset:61440
	s_waitcnt lgkmcnt(3)
	v_mfma_f32_16x16x32_bf16 v[92:95], v[124:127], v[92:95], 0
	s_mov_b64 s[18:19], -1
	s_and_b64 vcc, exec, s[48:49]
	s_waitcnt lgkmcnt(2)
	v_mfma_f32_16x16x32_bf16 v[92:95], v[128:131], v[96:99], v[92:95]
	s_waitcnt lgkmcnt(1)
	v_mfma_f32_16x16x32_bf16 v[96:99], v[136:139], v[100:103], v[92:95]
	s_waitcnt lgkmcnt(0)
	v_mfma_f32_16x16x32_bf16 v[88:91], v[132:135], v[88:91], v[96:99]
	s_nop 3
	ds_read_b128 v[92:95], v190 offset:448
	v_or_b32_e32 v136, 0x70, v189
	v_or_b32_e32 v137, 0x71, v189
	v_or_b32_e32 v138, 0x72, v189
	v_or_b32_e32 v139, 0x73, v189
	v_cmp_le_i32_e64 s[16:17], v136, v188
	v_cmp_le_i32_e64 s[18:19], v137, v188
	v_cmp_le_i32_e64 s[54:55], v138, v188
	v_cmp_le_i32_e64 s[50:51], v139, v188
	s_cbranch_vccnz .Lmk_done_7
	v_cndmask_b32_e64 v140, 1, 0, s[42:43]
	v_add_u32_e32 v140, v140, v188
	v_cmp_ge_i32_e64 s[16:17], v136, v140
	v_cmp_ge_i32_e64 s[18:19], v137, v140
	v_cmp_ge_i32_e64 s[54:55], v138, v140
	v_cmp_ge_i32_e64 s[50:51], v139, v140
.Lmk_done_7:
.LBB0_363:
	v_pk_mul_f32 v[148:149], v[76:77], v[158:159] op_sel_hi:[1,0]
	s_waitcnt lgkmcnt(0)
	v_add_f32_e32 v76, v171, v95
	v_add_f32_e32 v94, v171, v94
	v_add_f32_e32 v93, v171, v93
	v_add_f32_e32 v92, v171, v92
	v_exp_f32_e32 v76, v76
	v_exp_f32_e32 v94, v94
	v_exp_f32_e32 v93, v93
	v_exp_f32_e32 v92, v92
	v_mul_f32_e32 v76, v91, v76
	v_mul_f32_e32 v90, v90, v94
	v_mul_f32_e32 v89, v89, v93
	v_mul_f32_e32 v88, v88, v92
	v_pk_mul_f32 v[150:151], v[78:79], v[158:159] op_sel_hi:[1,0]
	v_cndmask_b32_e64 v77, 0, v76, s[50:51]
	v_mov_b32_e32 v78, v179
	v_cndmask_b32_e64 v90, 0, v90, s[54:55]
	v_cndmask_b32_e64 v89, 0, v89, s[18:19]
	v_cndmask_b32_e64 v88, 0, v88, s[16:17]
	v_cvt_pk_bf16_f32 v76, v88, v89
	v_cvt_pk_bf16_f32 v77, v90, v77
	v_pk_mul_f32 v[130:131], v[106:107], v[158:159] op_sel_hi:[1,0]
	v_pk_mul_f32 v[128:129], v[104:105], v[158:159] op_sel_hi:[1,0]
	v_pk_mul_f32 v[138:139], v[110:111], v[158:159] op_sel_hi:[1,0]
	v_pk_mul_f32 v[136:137], v[108:109], v[158:159] op_sel_hi:[1,0]
	v_pk_mul_f32 v[134:135], v[114:115], v[158:159] op_sel_hi:[1,0]
	v_pk_mul_f32 v[132:133], v[112:113], v[158:159] op_sel_hi:[1,0]
	v_pk_mul_f32 v[126:127], v[118:119], v[158:159] op_sel_hi:[1,0]
	v_pk_mul_f32 v[124:125], v[116:117], v[158:159] op_sel_hi:[1,0]
	v_pk_mul_f32 v[118:119], v[122:123], v[158:159] op_sel_hi:[1,0]
	v_pk_mul_f32 v[116:117], v[120:121], v[158:159] op_sel_hi:[1,0]
	v_xad_u32 v78, v78, s97, v191
	v_pk_mul_f32 v[146:147], v[82:83], v[158:159] op_sel_hi:[1,0]
	v_pk_mul_f32 v[144:145], v[80:81], v[158:159] op_sel_hi:[1,0]
	v_pk_mul_f32 v[142:143], v[86:87], v[158:159] op_sel_hi:[1,0]
	v_pk_mul_f32 v[140:141], v[84:85], v[158:159] op_sel_hi:[1,0]
	ds_write_b64 v78, v[76:77]
	ds_read_b128 v[100:103], v0
	ds_read_b128 v[88:91], v157
	ds_read_b128 v[84:87], v159
	ds_read_b128 v[76:79], v170
	ds_read_b64_tr_b16 v[96:97], v165 offset:32768
	ds_read_b64_tr_b16 v[98:99], v165 offset:40960
	ds_read_b64_tr_b16 v[104:105], v165 offset:49152
	ds_read_b64_tr_b16 v[112:113], v165 offset:57344
	ds_read_b64_tr_b16 v[106:107], v166 offset:33792
	ds_read_b64_tr_b16 v[114:115], v166 offset:41984
	ds_read_b64_tr_b16 v[120:121], v166 offset:50176
	ds_read_b64_tr_b16 v[122:123], v166 offset:58368
	ds_read_b128 v[80:83], v192
	ds_read_b128 v[92:95], v192 offset:16
	s_waitcnt lgkmcnt(9)
; #define LAS __attribute__((address_space(3)))
; __device__ __forceinline__ unsigned cvt_pk_bf16(float lo, float hi) { unsigned r; asm volatile("v_cvt_pk_bf16_f32 %0, %1, %2" : "=v"(r) : "v"(lo), "v"(hi)); return r; }
; #define TRFRAG(img, c, ks) trfrag_(lds, (img) + 256u * (32u * (ks)) + TRA(c, 0), (img) + 256u * (32u * (ks) + 4u) + TRA(c, 1))
; #define MFMA16(a, b, c) __builtin_amdgcn_mfma_f32_16x16x32_bf16((a), (b), (c), 0, 0, 0)
; __device__ void mix_sweep(const Params& P, LAS unsigned char* lds, int tok0, int pos0, int seqlen, int hd, int dir, bool state_only, bool final_pass,
;                           f32x4 (&Cacc)[9], float& m_state, float& aseg_sum, float lgam) {
;     ...
;             for (int ks = 0; ks < 4; ++ks) { const bf16x8 raw = kraw[ks];
;                 const f32x4 k0 = *(const LAS f32x4*)(vkw + 32 * ks + 8 * fg), k1 = *(const LAS f32x4*)(vkw + 32 * ks + 8 * fg + 4);
;                 float f[8];
; #pragma unroll
;                 for (int e = 0; e < 8; ++e) f[e] = __uint_as_float(((unsigned)(unsigned short)raw[e]) << 16) * (e < 4 ? k0[e] : k1[e - 4]);
;                 u32x4 pk; pk.x = cvt_pk_bf16(f[0], f[1]); pk.y = cvt_pk_bf16(f[2], f[3]); pk.z = cvt_pk_bf16(f[4], f[5]); pk.w = cvt_pk_bf16(f[6], f[7]);
;                 kf[ks] = __builtin_bit_cast(bf16x8, pk); }
;             __builtin_amdgcn_s_setprio(1);
; #pragma unroll
;             for (int nt = 0; nt < 8; ++nt) { LAUNDER_L16
;                 bf16x8 vf[4];
; #pragma unroll
;                 for (int ks = 0; ks < 4; ++ks) vf[ks] = TRFRAG(IMG_V, nt, ks);
;                 __builtin_amdgcn_sched_barrier(0);
;                 f32x4 a = Cacc[nt] * decay;
; #pragma unroll
;                 for (int ks = 0; ks < 4; ++ks) { O[nt] = MFMA16(vf[ks], pf[ks], O[nt]); a = MFMA16(vf[ks], kf[ks], a); }
;                 Cacc[nt] = a; }
;     ...
;                 const bf16_t* grow = proj + (size_t)(tok + irow) * NPROJ + gcol + 4 * fg;
;                 u32x2 hbv[8], gvv[8];
; #pragma unroll
;                 for (int nt = 0; nt < 8; ++nt) { hbv[nt] = *(const u32x2*)(mrow + 16 * nt); gvv[nt] = *(const u32x2*)(grow + 16 * nt); }
	v_lshlrev_b32_e32 v0, 16, v96
	v_and_b32_e32 v96, 0xffff0000, v96
	s_waitcnt lgkmcnt(1)
	v_mul_f32_e32 v0, v80, v0
	v_mul_f32_e32 v80, v81, v96
	v_lshlrev_b32_e32 v81, 16, v97
	v_mul_f32_e32 v81, v82, v81
	v_and_b32_e32 v82, 0xffff0000, v97
	v_mul_f32_e32 v82, v83, v82
	v_lshlrev_b32_e32 v83, 16, v106
	s_waitcnt lgkmcnt(0)
	v_mul_f32_e32 v83, v92, v83
	v_and_b32_e32 v92, 0xffff0000, v106
	v_mul_f32_e32 v92, v93, v92
	v_lshlrev_b32_e32 v93, 16, v107
	v_mul_f32_e32 v93, v94, v93
	v_and_b32_e32 v94, 0xffff0000, v107
	v_mul_f32_e32 v94, v95, v94
	v_cvt_pk_bf16_f32 v108, v0, v80
	v_cvt_pk_bf16_f32 v109, v81, v82
	v_cvt_pk_bf16_f32 v110, v83, v92
	v_cvt_pk_bf16_f32 v111, v93, v94
	ds_read_b128 v[80:83], v192 offset:128
	ds_read_b128 v[92:95], v192 offset:144
	v_lshlrev_b32_e32 v0, 16, v98
	s_waitcnt lgkmcnt(1)
	v_mul_f32_e32 v0, v80, v0
	v_and_b32_e32 v80, 0xffff0000, v98
	v_mul_f32_e32 v80, v81, v80
	v_lshlrev_b32_e32 v81, 16, v99
	v_mul_f32_e32 v81, v82, v81
	v_and_b32_e32 v82, 0xffff0000, v99
	v_mul_f32_e32 v82, v83, v82
	v_lshlrev_b32_e32 v83, 16, v114
	s_waitcnt lgkmcnt(0)
	v_mul_f32_e32 v83, v92, v83
	v_and_b32_e32 v92, 0xffff0000, v114
	v_mul_f32_e32 v96, v93, v92
	v_lshlrev_b32_e32 v92, 16, v115
	v_mul_f32_e32 v97, v94, v92
	v_and_b32_e32 v92, 0xffff0000, v115
	v_mul_f32_e32 v95, v95, v92
	v_cvt_pk_bf16_f32 v92, v0, v80
	v_cvt_pk_bf16_f32 v93, v81, v82
	v_cvt_pk_bf16_f32 v94, v83, v96
	v_cvt_pk_bf16_f32 v95, v97, v95
	ds_read_b128 v[80:83], v192 offset:256
	ds_read_b128 v[96:99], v192 offset:272
	v_lshlrev_b32_e32 v0, 16, v104
	s_waitcnt lgkmcnt(1)
	v_mul_f32_e32 v0, v80, v0
	v_and_b32_e32 v80, 0xffff0000, v104
	v_mul_f32_e32 v80, v81, v80
	v_lshlrev_b32_e32 v81, 16, v105
	v_mul_f32_e32 v81, v82, v81
	v_and_b32_e32 v82, 0xffff0000, v105
	v_mul_f32_e32 v82, v83, v82
	v_lshlrev_b32_e32 v83, 16, v120
	s_waitcnt lgkmcnt(0)
	v_mul_f32_e32 v83, v96, v83
	v_and_b32_e32 v96, 0xffff0000, v120
	v_mul_f32_e32 v96, v97, v96
	v_lshlrev_b32_e32 v97, 16, v121
	v_mul_f32_e32 v97, v98, v97
	v_and_b32_e32 v98, 0xffff0000, v121
	v_mul_f32_e32 v98, v99, v98
	v_cvt_pk_bf16_f32 v104, v0, v80
	v_cvt_pk_bf16_f32 v105, v81, v82
	v_cvt_pk_bf16_f32 v106, v83, v96
	v_cvt_pk_bf16_f32 v107, v97, v98
	ds_read_b128 v[80:83], v192 offset:384
	ds_read_b128 v[96:99], v192 offset:400
	v_lshlrev_b32_e32 v0, 16, v112
	s_waitcnt lgkmcnt(1)
	v_mul_f32_e32 v0, v80, v0
	v_and_b32_e32 v80, 0xffff0000, v112
	v_mul_f32_e32 v80, v81, v80
	v_lshlrev_b32_e32 v81, 16, v113
	v_mul_f32_e32 v81, v82, v81
	v_and_b32_e32 v82, 0xffff0000, v113
	v_mul_f32_e32 v82, v83, v82
	v_lshlrev_b32_e32 v83, 16, v122
	s_waitcnt lgkmcnt(0)
	v_mul_f32_e32 v83, v96, v83
	v_and_b32_e32 v96, 0xffff0000, v122
	v_mul_f32_e32 v112, v97, v96
	v_lshlrev_b32_e32 v96, 16, v123
	v_mul_f32_e32 v113, v98, v96
	v_and_b32_e32 v96, 0xffff0000, v123
	v_mul_f32_e32 v99, v99, v96
	v_cvt_pk_bf16_f32 v96, v0, v80
	v_cvt_pk_bf16_f32 v97, v81, v82
	v_cvt_pk_bf16_f32 v98, v83, v112
	v_cvt_pk_bf16_f32 v99, v113, v99
	s_and_b64 s[16:17], exec, s[48:49]
	s_cbranch_scc0 .Lmixpf_skip
	v_add_u32_e32 v244, s89, v188
	v_ashrrev_i32_e32 v245, 31, v244
	v_lshlrev_b64 v[242:243], 11, v[244:245]
	v_lshl_add_u64 v[242:243], v[2:3], 0, v[242:243]
	v_lshlrev_b64 v[244:245], 13, v[244:245]
	v_lshl_add_u64 v[244:245], v[152:153], 0, v[244:245]
	global_load_dwordx2 v[204:205], v[242:243], off
	global_load_dwordx2 v[206:207], v[242:243], off offset:32
	global_load_dwordx2 v[222:223], v[242:243], off offset:64
	global_load_dwordx2 v[224:225], v[242:243], off offset:96
	global_load_dwordx2 v[226:227], v[244:245], off
	global_load_dwordx2 v[228:229], v[244:245], off offset:32
	global_load_dwordx2 v[230:231], v[244:245], off offset:64
	global_load_dwordx2 v[232:233], v[244:245], off offset:96
	global_load_dwordx2 v[234:235], v[242:243], off offset:128
	global_load_dwordx2 v[236:237], v[242:243], off offset:160
	global_load_dwordx2 v[238:239], v[242:243], off offset:192
	global_load_dwordx2 v[240:241], v[242:243], off offset:224
.Lmixpf_skip:
	s_setprio 1
	v_mov_b32_e32 v0, v178
	s_nop 0
	v_xor_b32_e32 v120, 16, v0
	v_add_u32_e32 v80, v246, v0
	v_add_u32_e32 v82, v247, v120
	v_add_u32_e32 v112, v248, v0
	v_add_u32_e32 v114, v249, v120
	v_add_u32_e32 v121, v250, v0
	v_add_u32_e32 v122, v251, v120
	ds_read_b64_tr_b16 v[80:81], v80
	ds_read_b64_tr_b16 v[82:83], v82
	ds_read_b64_tr_b16 v[112:113], v112
	ds_read_b64_tr_b16 v[114:115], v114
	v_add_u32_e32 v0, v252, v0
	v_add_u32_e32 v157, v211, v120
	ds_read_b64_tr_b16 v[120:121], v121
	ds_read_b64_tr_b16 v[122:123], v122
	ds_read_b64_tr_b16 v[170:171], v0
	ds_read_b64_tr_b16 v[172:173], v157
	v_pk_mul_f32 v[34:35], v[34:35], v[156:157] op_sel_hi:[1,0]
	v_pk_mul_f32 v[32:33], v[32:33], v[156:157] op_sel_hi:[1,0]
	s_waitcnt lgkmcnt(6)
	v_mfma_f32_16x16x32_bf16 v[148:151], v[80:83], v[100:103], v[148:151]
	v_mov_b32_e32 v0, v178
	v_mfma_f32_16x16x32_bf16 v[32:35], v[80:83], v[108:111], v[32:35]
	v_xor_b32_e32 v157, 32, v0
	v_xor_b32_e32 v0, 48, v0
	s_waitcnt lgkmcnt(4)
	v_mfma_f32_16x16x32_bf16 v[80:83], v[112:115], v[88:91], v[148:151]
	v_mfma_f32_16x16x32_bf16 v[32:35], v[112:115], v[92:95], v[32:35]
	v_add_u32_e32 v112, v246, v157
	v_add_u32_e32 v114, v247, v0
	ds_read_b64_tr_b16 v[112:113], v112
	ds_read_b64_tr_b16 v[114:115], v114
	s_waitcnt lgkmcnt(4)
	v_mfma_f32_16x16x32_bf16 v[80:83], v[120:123], v[84:87], v[80:83]
	v_add_u32_e32 v148, v250, v157
	v_add_u32_e32 v150, v251, v0
	ds_read_b64_tr_b16 v[148:149], v148
	ds_read_b64_tr_b16 v[150:151], v150
	v_mfma_f32_16x16x32_bf16 v[32:35], v[120:123], v[104:107], v[32:35]
	v_add_u32_e32 v120, v248, v157
	v_add_u32_e32 v122, v249, v0
	ds_read_b64_tr_b16 v[120:121], v120
	ds_read_b64_tr_b16 v[122:123], v122
	v_add_u32_e32 v157, v252, v157
	v_add_u32_e32 v0, v211, v0
	s_waitcnt lgkmcnt(6)
; #define TRFRAG(img, c, ks) trfrag_(lds, (img) + 256u * (32u * (ks)) + TRA(c, 0), (img) + 256u * (32u * (ks) + 4u) + TRA(c, 1))
; #define MFMA16(a, b, c) __builtin_amdgcn_mfma_f32_16x16x32_bf16((a), (b), (c), 0, 0, 0)
; __device__ void mix_sweep(const Params& P, LAS unsigned char* lds, int tok0, int pos0, int seqlen, int hd, int dir, bool state_only, bool final_pass,
;                           f32x4 (&Cacc)[9], float& m_state, float& aseg_sum, float lgam) {
;     ...
;             for (int nt = 0; nt < 8; ++nt) { LAUNDER_L16
;                 bf16x8 vf[4];
; #pragma unroll
;                 for (int ks = 0; ks < 4; ++ks) vf[ks] = TRFRAG(IMG_V, nt, ks);
;                 __builtin_amdgcn_sched_barrier(0);
;                 f32x4 a = Cacc[nt] * decay;
; #pragma unroll
;                 for (int ks = 0; ks < 4; ++ks) { O[nt] = MFMA16(vf[ks], pf[ks], O[nt]); a = MFMA16(vf[ks], kf[ks], a); }
;                 Cacc[nt] = a; }
	v_mfma_f32_16x16x32_bf16 v[80:83], v[170:173], v[76:79], v[80:83]
	v_mfma_f32_16x16x32_bf16 v[32:35], v[170:173], v[96:99], v[32:35]
	ds_read_b64_tr_b16 v[170:171], v157
	ds_read_b64_tr_b16 v[172:173], v0
	v_pk_mul_f32 v[30:31], v[30:31], v[156:157] op_sel_hi:[1,0]
	v_pk_mul_f32 v[28:29], v[28:29], v[156:157] op_sel_hi:[1,0]
	s_waitcnt lgkmcnt(6)
	v_mfma_f32_16x16x32_bf16 v[144:147], v[112:115], v[100:103], v[144:147]
	v_mov_b32_e32 v0, v178
	v_mfma_f32_16x16x32_bf16 v[28:31], v[112:115], v[108:111], v[28:31]
	v_xor_b32_e32 v157, 64, v0
	v_xor_b32_e32 v0, 0x50, v0
	s_waitcnt lgkmcnt(2)
	v_mfma_f32_16x16x32_bf16 v[112:115], v[120:123], v[88:91], v[144:147]
	v_mfma_f32_16x16x32_bf16 v[28:31], v[120:123], v[92:95], v[28:31]
	v_add_u32_e32 v120, v246, v157
	v_add_u32_e32 v122, v247, v0
	ds_read_b64_tr_b16 v[120:121], v120
	ds_read_b64_tr_b16 v[122:123], v122
	v_mfma_f32_16x16x32_bf16 v[112:115], v[148:151], v[84:87], v[112:115]
	v_add_u32_e32 v144, v248, v157
	v_add_u32_e32 v146, v249, v0
	ds_read_b64_tr_b16 v[144:145], v144
	v_mfma_f32_16x16x32_bf16 v[28:31], v[148:151], v[104:107], v[28:31]
	v_add_u32_e32 v148, v250, v157
	v_add_u32_e32 v150, v251, v0
	v_add_u32_e32 v157, v252, v157
	v_add_u32_e32 v0, v211, v0
	s_waitcnt lgkmcnt(3)
	v_mfma_f32_16x16x32_bf16 v[112:115], v[170:173], v[76:79], v[112:115]
	ds_read_b64_tr_b16 v[146:147], v146
	ds_read_b64_tr_b16 v[148:149], v148
	ds_read_b64_tr_b16 v[150:151], v150
	v_mfma_f32_16x16x32_bf16 v[28:31], v[170:173], v[96:99], v[28:31]
	ds_read_b64_tr_b16 v[170:171], v157
	ds_read_b64_tr_b16 v[172:173], v0
	v_pk_mul_f32 v[26:27], v[26:27], v[156:157] op_sel_hi:[1,0]
	v_pk_mul_f32 v[24:25], v[24:25], v[156:157] op_sel_hi:[1,0]
	s_waitcnt lgkmcnt(6)
	v_mfma_f32_16x16x32_bf16 v[140:143], v[120:123], v[100:103], v[140:143]
	v_mov_b32_e32 v0, v178
	v_mfma_f32_16x16x32_bf16 v[24:27], v[120:123], v[108:111], v[24:27]
	v_xor_b32_e32 v157, 0x60, v0
	v_xor_b32_e32 v0, 0x70, v0
	s_waitcnt lgkmcnt(4)
	v_mfma_f32_16x16x32_bf16 v[120:123], v[144:147], v[88:91], v[140:143]
	v_mfma_f32_16x16x32_bf16 v[24:27], v[144:147], v[92:95], v[24:27]
	s_nop 1
	v_add_u32_e32 v140, v246, v157
	v_add_u32_e32 v142, v247, v0
	v_add_u32_e32 v144, v248, v157
	s_waitcnt lgkmcnt(2)
	v_mfma_f32_16x16x32_bf16 v[120:123], v[148:151], v[84:87], v[120:123]
	v_add_u32_e32 v146, v249, v0
	ds_read_b64_tr_b16 v[140:141], v140
	ds_read_b64_tr_b16 v[142:143], v142
	ds_read_b64_tr_b16 v[144:145], v144
	v_mfma_f32_16x16x32_bf16 v[24:27], v[148:151], v[104:107], v[24:27]
	v_add_u32_e32 v148, v250, v157
	v_add_u32_e32 v150, v251, v0
	v_add_u32_e32 v157, v252, v157
	v_add_u32_e32 v0, v211, v0
	s_waitcnt lgkmcnt(3)
	v_mfma_f32_16x16x32_bf16 v[120:123], v[170:173], v[76:79], v[120:123]
	ds_read_b64_tr_b16 v[146:147], v146
	ds_read_b64_tr_b16 v[148:149], v148
	ds_read_b64_tr_b16 v[150:151], v150
	v_mfma_f32_16x16x32_bf16 v[24:27], v[170:173], v[96:99], v[24:27]
	ds_read_b64_tr_b16 v[170:171], v157
	ds_read_b64_tr_b16 v[172:173], v0
	v_pk_mul_f32 v[22:23], v[22:23], v[156:157] op_sel_hi:[1,0]
	v_pk_mul_f32 v[20:21], v[20:21], v[156:157] op_sel_hi:[1,0]
	s_waitcnt lgkmcnt(6)
	v_mfma_f32_16x16x32_bf16 v[128:131], v[140:143], v[100:103], v[128:131]
	v_mov_b32_e32 v0, v178
	v_mfma_f32_16x16x32_bf16 v[20:23], v[140:143], v[108:111], v[20:23]
	v_xor_b32_e32 v157, 0x80, v0
	v_xor_b32_e32 v0, 0x90, v0
	v_add_u32_e32 v140, v246, v157
	s_waitcnt lgkmcnt(4)
	v_mfma_f32_16x16x32_bf16 v[128:131], v[144:147], v[88:91], v[128:131]
	v_add_u32_e32 v142, v247, v0
	ds_read_b64_tr_b16 v[140:141], v140
	ds_read_b64_tr_b16 v[142:143], v142
	v_mfma_f32_16x16x32_bf16 v[20:23], v[144:147], v[92:95], v[20:23]
	v_add_u32_e32 v144, v248, v157
	v_add_u32_e32 v146, v249, v0
	ds_read_b64_tr_b16 v[144:145], v144
	s_waitcnt lgkmcnt(5)
	v_mfma_f32_16x16x32_bf16 v[128:131], v[148:151], v[84:87], v[128:131]
	ds_read_b64_tr_b16 v[146:147], v146
	v_mfma_f32_16x16x32_bf16 v[20:23], v[148:151], v[104:107], v[20:23]
	v_add_u32_e32 v148, v250, v157
	v_add_u32_e32 v150, v251, v0
	v_add_u32_e32 v157, v252, v157
	v_add_u32_e32 v0, v211, v0
	s_waitcnt lgkmcnt(4)
	v_mfma_f32_16x16x32_bf16 v[128:131], v[170:173], v[76:79], v[128:131]
	ds_read_b64_tr_b16 v[148:149], v148
	ds_read_b64_tr_b16 v[150:151], v150
	v_mfma_f32_16x16x32_bf16 v[20:23], v[170:173], v[96:99], v[20:23]
	ds_read_b64_tr_b16 v[170:171], v157
	ds_read_b64_tr_b16 v[172:173], v0
	v_pk_mul_f32 v[18:19], v[18:19], v[156:157] op_sel_hi:[1,0]
	v_pk_mul_f32 v[16:17], v[16:17], v[156:157] op_sel_hi:[1,0]
	s_waitcnt lgkmcnt(6)
	v_mfma_f32_16x16x32_bf16 v[136:139], v[140:143], v[100:103], v[136:139]
	v_mov_b32_e32 v0, v178
	v_mfma_f32_16x16x32_bf16 v[16:19], v[140:143], v[108:111], v[16:19]
	v_xor_b32_e32 v157, 0xa0, v0
	v_xor_b32_e32 v0, 0xb0, v0
	v_add_u32_e32 v140, v246, v157
	s_waitcnt lgkmcnt(4)
; #define TRFRAG(img, c, ks) trfrag_(lds, (img) + 256u * (32u * (ks)) + TRA(c, 0), (img) + 256u * (32u * (ks) + 4u) + TRA(c, 1))
; #define TRFRAGX(img, ks) trfrag_(lds, (img) + 32u * (32u * (ks)) + FB.txb, (img) + 32u * (32u * (ks) + 4u) + FB.txb)
; #define MFMA16(a, b, c) __builtin_amdgcn_mfma_f32_16x16x32_bf16((a), (b), (c), 0, 0, 0)
; __device__ void mix_sweep(const Params& P, LAS unsigned char* lds, int tok0, int pos0, int seqlen, int hd, int dir, bool state_only, bool final_pass,
;                           f32x4 (&Cacc)[9], float& m_state, float& aseg_sum, float lgam) {
;     ...
;             for (int nt = 0; nt < 8; ++nt) { LAUNDER_L16
;                 bf16x8 vf[4];
; #pragma unroll
;                 for (int ks = 0; ks < 4; ++ks) vf[ks] = TRFRAG(IMG_V, nt, ks);
;                 __builtin_amdgcn_sched_barrier(0);
;                 f32x4 a = Cacc[nt] * decay;
; #pragma unroll
;                 for (int ks = 0; ks < 4; ++ks) { O[nt] = MFMA16(vf[ks], pf[ks], O[nt]); a = MFMA16(vf[ks], kf[ks], a); }
;                 Cacc[nt] = a; }
;             if (is_m) { f32x4 a = Cacc[8] * decay;
; #pragma unroll
;                 for (int ks = 0; ks < 4; ++ks) { const bf16x8 vx = TRFRAGX(IMG_VX, ks); O[8] = MFMA16(vx, pf[ks], O[8]); a = MFMA16(vx, kf[ks], a); }
;                 Cacc[8] = a; }
;             __builtin_amdgcn_s_setprio(0);
	v_mfma_f32_16x16x32_bf16 v[136:139], v[144:147], v[88:91], v[136:139]
	v_add_u32_e32 v142, v247, v0
	ds_read_b64_tr_b16 v[140:141], v140
	ds_read_b64_tr_b16 v[142:143], v142
	v_mfma_f32_16x16x32_bf16 v[16:19], v[144:147], v[92:95], v[16:19]
	v_add_u32_e32 v144, v248, v157
	v_add_u32_e32 v146, v249, v0
	ds_read_b64_tr_b16 v[144:145], v144
	s_waitcnt lgkmcnt(5)
	v_mfma_f32_16x16x32_bf16 v[136:139], v[148:151], v[84:87], v[136:139]
	ds_read_b64_tr_b16 v[146:147], v146
	v_mfma_f32_16x16x32_bf16 v[16:19], v[148:151], v[104:107], v[16:19]
	v_add_u32_e32 v148, v250, v157
	v_add_u32_e32 v150, v251, v0
	v_add_u32_e32 v157, v252, v157
	v_add_u32_e32 v0, v211, v0
	s_waitcnt lgkmcnt(4)
	v_mfma_f32_16x16x32_bf16 v[136:139], v[170:173], v[76:79], v[136:139]
	ds_read_b64_tr_b16 v[148:149], v148
	ds_read_b64_tr_b16 v[150:151], v150
	v_mfma_f32_16x16x32_bf16 v[16:19], v[170:173], v[96:99], v[16:19]
	ds_read_b64_tr_b16 v[170:171], v157
	ds_read_b64_tr_b16 v[172:173], v0
	v_pk_mul_f32 v[14:15], v[14:15], v[156:157] op_sel_hi:[1,0]
	v_pk_mul_f32 v[12:13], v[12:13], v[156:157] op_sel_hi:[1,0]
	s_waitcnt lgkmcnt(6)
	v_mfma_f32_16x16x32_bf16 v[132:135], v[140:143], v[100:103], v[132:135]
	v_mov_b32_e32 v0, v178
	v_mfma_f32_16x16x32_bf16 v[12:15], v[140:143], v[108:111], v[12:15]
	v_xor_b32_e32 v157, 0xc0, v0
	v_xor_b32_e32 v0, 0xd0, v0
	v_add_u32_e32 v140, v246, v157
	s_waitcnt lgkmcnt(4)
	v_mfma_f32_16x16x32_bf16 v[132:135], v[144:147], v[88:91], v[132:135]
	v_add_u32_e32 v142, v247, v0
	ds_read_b64_tr_b16 v[140:141], v140
	ds_read_b64_tr_b16 v[142:143], v142
	v_mfma_f32_16x16x32_bf16 v[12:15], v[144:147], v[92:95], v[12:15]
	v_add_u32_e32 v144, v248, v157
	v_add_u32_e32 v146, v249, v0
	ds_read_b64_tr_b16 v[144:145], v144
	s_waitcnt lgkmcnt(5)
	v_mfma_f32_16x16x32_bf16 v[132:135], v[148:151], v[84:87], v[132:135]
	ds_read_b64_tr_b16 v[146:147], v146
	v_mfma_f32_16x16x32_bf16 v[12:15], v[148:151], v[104:107], v[12:15]
	v_add_u32_e32 v148, v250, v157
	v_add_u32_e32 v150, v251, v0
	v_add_u32_e32 v157, v252, v157
	v_add_u32_e32 v0, v211, v0
	s_waitcnt lgkmcnt(4)
	v_mfma_f32_16x16x32_bf16 v[132:135], v[170:173], v[76:79], v[132:135]
	ds_read_b64_tr_b16 v[148:149], v148
	ds_read_b64_tr_b16 v[150:151], v150
	v_mfma_f32_16x16x32_bf16 v[12:15], v[170:173], v[96:99], v[12:15]
	ds_read_b64_tr_b16 v[170:171], v157
	ds_read_b64_tr_b16 v[172:173], v0
	v_pk_mul_f32 v[10:11], v[10:11], v[156:157] op_sel_hi:[1,0]
	v_pk_mul_f32 v[8:9], v[8:9], v[156:157] op_sel_hi:[1,0]
	s_waitcnt lgkmcnt(6)
	v_mfma_f32_16x16x32_bf16 v[124:127], v[140:143], v[100:103], v[124:127]
	v_mov_b32_e32 v0, v178
	v_mfma_f32_16x16x32_bf16 v[8:11], v[140:143], v[108:111], v[8:11]
	v_xor_b32_e32 v157, 0xe0, v0
	v_xor_b32_e32 v0, 0xf0, v0
	v_add_u32_e32 v140, v246, v157
	s_waitcnt lgkmcnt(4)
	v_mfma_f32_16x16x32_bf16 v[124:127], v[144:147], v[88:91], v[124:127]
	v_add_u32_e32 v142, v247, v0
	ds_read_b64_tr_b16 v[140:141], v140
	ds_read_b64_tr_b16 v[142:143], v142
	v_mfma_f32_16x16x32_bf16 v[8:11], v[144:147], v[92:95], v[8:11]
	v_add_u32_e32 v144, v248, v157
	v_add_u32_e32 v146, v249, v0
	ds_read_b64_tr_b16 v[144:145], v144
	s_waitcnt lgkmcnt(5)
	v_mfma_f32_16x16x32_bf16 v[124:127], v[148:151], v[84:87], v[124:127]
	ds_read_b64_tr_b16 v[146:147], v146
	v_mfma_f32_16x16x32_bf16 v[8:11], v[148:151], v[104:107], v[8:11]
	v_add_u32_e32 v148, v250, v157
	v_add_u32_e32 v150, v251, v0
	v_add_u32_e32 v157, v252, v157
	v_add_u32_e32 v0, v211, v0
	s_waitcnt lgkmcnt(4)
	v_mfma_f32_16x16x32_bf16 v[124:127], v[170:173], v[76:79], v[124:127]
	ds_read_b64_tr_b16 v[148:149], v148
	ds_read_b64_tr_b16 v[150:151], v150
	v_mfma_f32_16x16x32_bf16 v[8:11], v[170:173], v[96:99], v[8:11]
	ds_read_b64_tr_b16 v[170:171], v157
	ds_read_b64_tr_b16 v[172:173], v0
	v_pk_mul_f32 v[6:7], v[6:7], v[156:157] op_sel_hi:[1,0]
	v_pk_mul_f32 v[4:5], v[4:5], v[156:157] op_sel_hi:[1,0]
	s_waitcnt lgkmcnt(6)
	v_mfma_f32_16x16x32_bf16 v[116:119], v[140:143], v[100:103], v[116:119]
	s_mov_b64 s[16:17], -1
	s_and_b64 vcc, exec, s[92:93]
	v_mfma_f32_16x16x32_bf16 v[4:7], v[140:143], v[108:111], v[4:7]
	s_waitcnt lgkmcnt(4)
	v_mfma_f32_16x16x32_bf16 v[116:119], v[144:147], v[88:91], v[116:119]
	v_mfma_f32_16x16x32_bf16 v[4:7], v[144:147], v[92:95], v[4:7]
	s_waitcnt lgkmcnt(2)
	v_mfma_f32_16x16x32_bf16 v[116:119], v[148:151], v[84:87], v[116:119]
	v_mfma_f32_16x16x32_bf16 v[4:7], v[148:151], v[104:107], v[4:7]
	s_waitcnt lgkmcnt(0)
	v_mfma_f32_16x16x32_bf16 v[116:119], v[170:173], v[76:79], v[116:119]
	v_mfma_f32_16x16x32_bf16 v[4:7], v[170:173], v[96:99], v[4:7]
	s_cbranch_vccz .LBB0_365
	s_setprio 0
	s_mov_b64 s[16:17], 0

; __device__ __forceinline__ unsigned cvt_pk_bf16(float lo, float hi) { unsigned r; asm volatile("v_cvt_pk_bf16_f32 %0, %1, %2" : "=v"(r) : "v"(lo), "v"(hi)); return r; }
; __device__ __forceinline__ float bf_lo(unsigned w) { return __uint_as_float(w << 16); }
; __device__ __forceinline__ float bf_hi(unsigned w) { return __uint_as_float(w & 0xffff0000u); }
; __device__ void mix_sweep(const Params& P, LAS unsigned char* lds, int tok0, int pos0, int seqlen, int hd, int dir, bool state_only, bool final_pass,
;                           f32x4 (&Cacc)[9], float& m_state, float& aseg_sum, float lgam) {
;     ...
;             if (!final_pass) {
; #pragma unroll
;                 for (int nt = 0; nt < 8; ++nt) { u32x2 v; v.x = cvt_pk_bf16(O[nt][0] * hs, O[nt][1] * hs); v.y = cvt_pk_bf16(O[nt][2] * hs, O[nt][3] * hs); *(u32x2*)(mrow + 16 * nt) = v; }
;             } else {
;                 float sum = 0.f;
;                 const bf16_t* grow = proj + (size_t)(tok + irow) * NPROJ + gcol + 4 * fg;
;                 u32x2 hbv[8], gvv[8];
; #pragma unroll
;                 for (int nt = 0; nt < 8; ++nt) { hbv[nt] = *(const u32x2*)(mrow + 16 * nt); gvv[nt] = *(const u32x2*)(grow + 16 * nt); }
;                 __builtin_amdgcn_sched_barrier(0);
; #pragma unroll
;                 for (int nt = 0; nt < 8; ++nt) { const u32x2 hb = hbv[nt];
;                     O[nt][0] = O[nt][0] * hs + bf_lo(hb.x); O[nt][1] = O[nt][1] * hs + bf_hi(hb.x); O[nt][2] = O[nt][2] * hs + bf_lo(hb.y); O[nt][3] = O[nt][3] * hs + bf_hi(hb.y);
;                     sum += O[nt][0] + O[nt][1] + O[nt][2] + O[nt][3]; }
;                 sum += __shfl_xor(sum, 16); sum += __shfl_xor(sum, 32);
;                 const float mu = sum * (1.0f / 128.0f); float sq = 0.f;
; #pragma unroll
;                 for (int nt = 0; nt < 8; ++nt)
; #pragma unroll
;                     for (int e = 0; e < 4; ++e) { const float d = O[nt][e] - mu; sq += d * d; }
;                 sq += __shfl_xor(sq, 16); sq += __shfl_xor(sq, 32);
;                 const float rs = rsqrtf(sq * (1.0f / 128.0f) + 1e-5f);
.LBB0_369:
	s_andn2_b64 vcc, exec, s[16:17]
	s_cbranch_vccnz .LBB0_97
	v_lshlrev_b64 v[74:75], 13, v[74:75]
	v_lshl_add_u64 v[74:75], v[152:153], 0, v[74:75]
	global_load_dwordx2 v[94:95], v[74:75], off offset:128
	global_load_dwordx2 v[84:85], v[74:75], off offset:160
	global_load_dwordx2 v[76:77], v[74:75], off offset:192
	global_load_dwordx2 v[74:75], v[74:75], off offset:224
	s_waitcnt vmcnt(4)
	v_mov_b64_e32 v[88:89], v[204:205]
	v_mov_b64_e32 v[92:93], v[206:207]
	v_mov_b64_e32 v[96:97], v[222:223]
	v_mov_b64_e32 v[98:99], v[224:225]
	v_mov_b64_e32 v[148:149], v[226:227]
	v_mov_b64_e32 v[146:147], v[228:229]
	v_mov_b64_e32 v[110:111], v[230:231]
	v_mov_b64_e32 v[104:105], v[232:233]
	v_mov_b64_e32 v[150:151], v[234:235]
	v_mov_b64_e32 v[156:157], v[236:237]
	v_mov_b64_e32 v[158:159], v[238:239]
	v_mov_b64_e32 v[170:171], v[240:241]
	s_nop 0
	v_mov_b32_e32 v100, v80
	v_mov_b32_e32 v101, v112
	s_waitcnt vmcnt(14)
	v_lshlrev_b32_e32 v103, 16, v92
	v_lshlrev_b32_e32 v102, 16, v88
	v_mov_b32_e32 v112, v81
	v_and_b32_e32 v81, 0xffff0000, v92
	v_and_b32_e32 v80, 0xffff0000, v88
	v_pk_fma_f32 v[144:145], v[100:101], v[0:1], v[102:103] op_sel_hi:[1,0,1]
	v_pk_fma_f32 v[142:143], v[112:113], v[0:1], v[80:81] op_sel_hi:[1,0,1]
	v_mov_b32_e32 v80, v82
	v_mov_b32_e32 v81, v114
	v_lshlrev_b32_e32 v101, 16, v93
	v_lshlrev_b32_e32 v100, 16, v89
	v_pk_fma_f32 v[140:141], v[80:81], v[0:1], v[100:101] op_sel_hi:[1,0,1]
	v_mov_b32_e32 v114, v83
	v_and_b32_e32 v81, 0xffff0000, v93
	v_and_b32_e32 v80, 0xffff0000, v89
	v_pk_fma_f32 v[114:115], v[114:115], v[0:1], v[80:81] op_sel_hi:[1,0,1]
	v_pk_add_f32 v[80:81], v[144:145], v[142:143]
	s_waitcnt vmcnt(12)
	v_lshlrev_b32_e32 v90, 16, v98
	v_pk_add_f32 v[80:81], v[140:141], v[80:81]
	v_and_b32_e32 v106, 0xffff0000, v98
	v_pk_add_f32 v[80:81], v[114:115], v[80:81]
	v_fmac_f32_e32 v90, v128, v0
	v_add_f32_e32 v80, 0, v80
	v_add_f32_e32 v86, v80, v81
	v_lshlrev_b32_e32 v80, 16, v96
	v_and_b32_e32 v81, 0xffff0000, v96
	v_pk_fma_f32 v[112:113], v[120:121], v[0:1], v[80:81] op_sel_hi:[1,0,1]
	v_and_b32_e32 v81, 0xffff0000, v97
	v_lshlrev_b32_e32 v80, 16, v97
	v_pk_fma_f32 v[108:109], v[122:123], v[0:1], v[80:81] op_sel_hi:[1,0,1]
	v_pk_add_f32 v[80:81], v[112:113], v[112:113] op_sel:[0,1] op_sel_hi:[1,0]
	v_fmac_f32_e32 v106, v129, v0
	v_pk_add_f32 v[80:81], v[108:109], v[80:81]
	s_waitcnt vmcnt(7)
	v_and_b32_e32 v107, 0xffff0000, v150
	v_and_b32_e32 v92, 0xffff0000, v151
	v_mov_b32_e32 v82, v130
	v_mov_b32_e32 v83, v136
	v_lshlrev_b32_e32 v89, 16, v150
	v_lshlrev_b32_e32 v88, 16, v99
	v_pk_add_f32 v[80:81], v[108:109], v[80:81] op_sel:[1,0] op_sel_hi:[0,1]
	v_pk_fma_f32 v[102:103], v[82:83], v[0:1], v[88:89] op_sel_hi:[1,0,1]
	v_pk_add_f32 v[100:101], v[90:91], v[106:107]
	v_pk_mov_b32 v[82:83], v[130:131], v[138:139] op_sel:[1,0]
	v_and_b32_e32 v88, 0xffff0000, v99
	v_lshlrev_b32_e32 v89, 16, v151
	v_mov_b32_e32 v81, v92
	v_pk_fma_f32 v[96:97], v[82:83], v[0:1], v[88:89] op_sel_hi:[1,0,1]
	v_pk_add_f32 v[92:93], v[86:87], v[80:81]
	v_pk_add_f32 v[80:81], v[102:103], v[100:101]
	s_waitcnt vmcnt(4)
	v_and_b32_e32 v91, 0xffff0000, v171
	v_pk_add_f32 v[80:81], v[96:97], v[80:81]
	v_mov_b32_e32 v120, v126
	v_pk_add_f32 v[82:83], v[92:93], v[80:81]
	v_lshlrev_b32_e32 v80, 16, v156
	v_and_b32_e32 v81, 0xffff0000, v156
	v_pk_fma_f32 v[86:87], v[132:133], v[0:1], v[80:81] op_sel_hi:[1,0,1]
	v_and_b32_e32 v81, 0xffff0000, v157
	v_lshlrev_b32_e32 v80, 16, v157
	v_pk_fma_f32 v[80:81], v[134:135], v[0:1], v[80:81] op_sel_hi:[1,0,1]
	v_pk_add_f32 v[88:89], v[86:87], v[86:87] op_sel:[0,1] op_sel_hi:[1,0]
	v_pk_add_f32 v[82:83], v[82:83], v[82:83] op_sel:[0,1] op_sel_hi:[1,0]
	v_pk_add_f32 v[88:89], v[80:81], v[88:89]
	v_mov_b32_e32 v121, v116
	v_pk_add_f32 v[88:89], v[80:81], v[88:89] op_sel:[1,0] op_sel_hi:[0,1]
	v_lshlrev_b32_e32 v117, 16, v170
	v_lshlrev_b32_e32 v116, 16, v159
	v_mov_b32_e32 v83, v78
	v_mov_b32_e32 v89, v91
	v_pk_fma_f32 v[120:121], v[120:121], v[0:1], v[116:117] op_sel_hi:[1,0,1]
	v_pk_mov_b32 v[116:117], v[126:127], v[118:119] op_sel:[1,0]
	v_pk_add_f32 v[126:127], v[82:83], v[88:89]
	v_and_b32_e32 v82, 64, v203
	v_xor_b32_e32 v78, 16, v203
	v_add_u32_e32 v91, 64, v82
	v_cmp_lt_i32_e32 vcc, v78, v91
	v_and_b32_e32 v83, 0xffff0000, v158
	v_lshlrev_b32_e32 v82, 16, v158
	v_cndmask_b32_e32 v78, v203, v78, vcc
	v_pk_fma_f32 v[82:83], v[124:125], v[0:1], v[82:83] op_sel_hi:[1,0,1]
	v_and_b32_e32 v99, 0xffff0000, v170
	v_lshlrev_b32_e32 v100, 2, v78
	v_mov_b32_e32 v78, v82
	v_mov_b32_e32 v98, v83
	v_and_b32_e32 v118, 0xffff0000, v159
	v_lshlrev_b32_e32 v119, 16, v171
	v_pk_add_f32 v[78:79], v[78:79], v[98:99]
	v_pk_fma_f32 v[122:123], v[116:117], v[0:1], v[118:119] op_sel_hi:[1,0,1]
	v_pk_add_f32 v[88:89], v[120:121], v[78:79]
	v_bfe_u32 v116, v161, 4, 2
	v_lshlrev_b32_e32 v116, 4, v116
	v_add_u32_e32 v116, 0x25a80, v116
	ds_read_b128 v[116:119], v116
	v_pk_add_f32 v[88:89], v[122:123], v[88:89]
	s_nop 0
	v_pk_add_f32 v[88:89], v[126:127], v[88:89]
	s_nop 0
	v_add_f32_e32 v0, v88, v89
	ds_bpermute_b32 v78, v100, v0
	v_xor_b32_e32 v88, 32, v203
	v_cmp_lt_i32_e32 vcc, v88, v91
	s_waitcnt lgkmcnt(0)
	v_add_f32_e32 v0, v0, v78
	v_cndmask_b32_e32 v88, v203, v88, vcc
	v_lshlrev_b32_e32 v107, 2, v88
	ds_bpermute_b32 v78, v107, v0
	s_waitcnt lgkmcnt(0)
; __device__ __forceinline__ unsigned cvt_pk_bf16(float lo, float hi) { unsigned r; asm volatile("v_cvt_pk_bf16_f32 %0, %1, %2" : "=v"(r) : "v"(lo), "v"(hi)); return r; }
; __device__ __forceinline__ float bf_lo(unsigned w) { return __uint_as_float(w << 16); }
; __device__ __forceinline__ float bf_hi(unsigned w) { return __uint_as_float(w & 0xffff0000u); }
; __device__ __forceinline__ float sigmoidf_(float x) { return 1.0f / (1.0f + __expf(-x)); }
; __device__ void mix_sweep(const Params& P, LAS unsigned char* lds, int tok0, int pos0, int seqlen, int hd, int dir, bool state_only, bool final_pass,
;                           f32x4 (&Cacc)[9], float& m_state, float& aseg_sum, float lgam) {
;     ...
;                 sum += __shfl_xor(sum, 16); sum += __shfl_xor(sum, 32);
;                 const float mu = sum * (1.0f / 128.0f); float sq = 0.f;
; #pragma unroll
;                 for (int nt = 0; nt < 8; ++nt)
; #pragma unroll
;                     for (int e = 0; e < 4; ++e) { const float d = O[nt][e] - mu; sq += d * d; }
;                 sq += __shfl_xor(sq, 16); sq += __shfl_xor(sq, 32);
;                 const float rs = rsqrtf(sq * (1.0f / 128.0f) + 1e-5f);
; #pragma unroll
;                 for (int nt = 0; nt < 8; ++nt) { const u32x2 gv = gvv[nt]; const f32x4 gw = *(const f32x4*)(gnw + 16 * nt + 4 * fg);
;                     float gt[4] = {bf_lo(gv.x), bf_hi(gv.x), bf_lo(gv.y), bf_hi(gv.y)}; float y[4];
; #pragma unroll
;                     for (int e = 0; e < 4; ++e) { const float sg = sigmoidf_(gt[e]); const float gate = is_m ? sg : gt[e] * sg; y[e] = (O[nt][e] - mu) * rs * gw[e] * gate; }
;                     u32x2 v; v.x = cvt_pk_bf16(y[0], y[1]); v.y = cvt_pk_bf16(y[2], y[3]); *(u32x2*)(mrow + 16 * nt) = v; }
	v_add_f32_e32 v78, v0, v78
	v_fmamk_f32 v125, v78, 0xbc000000, v142
	v_fmamk_f32 v124, v78, 0xbc000000, v144
	v_mul_f32_e32 v88, v125, v125
	v_fmac_f32_e32 v88, v124, v124
	v_fmamk_f32 v126, v78, 0xbc000000, v140
	v_fmac_f32_e32 v88, v126, v126
	v_fmamk_f32 v114, v78, 0xbc000000, v114
	v_fmac_f32_e32 v88, v114, v114
	v_fmac_f32_e32 v145, 0xbc000000, v78
	v_fmac_f32_e32 v88, v145, v145
	v_fmac_f32_e32 v143, 0xbc000000, v78
	v_fmac_f32_e32 v88, v143, v143
	v_fmac_f32_e32 v141, 0xbc000000, v78
	v_fmac_f32_e32 v88, v141, v141
	v_fmac_f32_e32 v115, 0xbc000000, v78
	v_fmac_f32_e32 v88, v115, v115
	v_fmamk_f32 v112, v78, 0xbc000000, v112
	v_fmac_f32_e32 v88, v112, v112
	v_fmac_f32_e32 v113, 0xbc000000, v78
	v_fmac_f32_e32 v88, v113, v113
	v_fmamk_f32 v108, v78, 0xbc000000, v108
	v_fmac_f32_e32 v88, v108, v108
	v_fmac_f32_e32 v109, 0xbc000000, v78
	v_fmac_f32_e32 v88, v109, v109
	v_fmac_f32_e32 v90, 0xbc000000, v78
	v_fmac_f32_e32 v88, v90, v90
	v_fmac_f32_e32 v106, 0xbc000000, v78
	v_fmac_f32_e32 v88, v106, v106
	v_fmamk_f32 v92, v78, 0xbc000000, v102
	v_fmac_f32_e32 v88, v92, v92
	v_fmamk_f32 v91, v78, 0xbc000000, v96
	v_fmac_f32_e32 v88, v91, v91
	v_fmac_f32_e32 v103, 0xbc000000, v78
	v_fmac_f32_e32 v88, v103, v103
	v_fmac_f32_e32 v101, 0xbc000000, v78
	v_fmac_f32_e32 v88, v101, v101
	v_fmac_f32_e32 v97, 0xbc000000, v78
	v_fmac_f32_e32 v88, v97, v97
	v_fmac_f32_e32 v93, 0xbc000000, v78
	v_fmac_f32_e32 v88, v93, v93
	v_fmamk_f32 v86, v78, 0xbc000000, v86
	v_fmac_f32_e32 v88, v86, v86
	v_fmac_f32_e32 v87, 0xbc000000, v78
	v_mul_f32_e32 v0, 0x3c000000, v78
	v_fmac_f32_e32 v88, v87, v87
	v_fmamk_f32 v80, v78, 0xbc000000, v80
	v_fmac_f32_e32 v88, v80, v80
	v_fmac_f32_e32 v81, 0xbc000000, v78
	v_pk_add_f32 v[98:99], v[82:83], v[0:1] op_sel_hi:[1,0] neg_lo:[0,1] neg_hi:[0,1]
	v_fmac_f32_e32 v88, v81, v81
	v_pk_mul_f32 v[82:83], v[98:99], v[98:99]
	s_nop 0
	v_add_f32_e32 v78, v82, v88
	v_add_f32_e32 v78, v83, v78
	v_mov_b32_e32 v82, v122
	v_mov_b32_e32 v83, v120
	v_pk_add_f32 v[88:89], v[82:83], v[0:1] op_sel_hi:[1,0] neg_lo:[0,1] neg_hi:[0,1]
	v_mov_b32_e32 v120, v79
	v_pk_mul_f32 v[82:83], v[88:89], v[88:89]
	v_mov_b32_e32 v122, v127
	v_add_f32_e32 v78, v83, v78
	v_add_f32_e32 v96, v82, v78
	v_pk_add_f32 v[82:83], v[120:121], v[0:1] op_sel_hi:[1,0] neg_lo:[0,1] neg_hi:[0,1]
	s_nop 0
	v_pk_mul_f32 v[78:79], v[82:83], v[82:83]
	s_nop 0
	v_add_f32_e32 v79, v79, v96
	v_add_f32_e32 v96, v78, v79
	v_pk_add_f32 v[78:79], v[122:123], v[0:1] op_sel_hi:[1,0] neg_lo:[0,1] neg_hi:[0,1]
	v_and_b32_e32 v122, 0xffff0000, v149
	v_pk_mul_f32 v[120:121], v[78:79], v[78:79]
	s_nop 0
	v_add_f32_e32 v0, v121, v96
	v_add_f32_e32 v0, v120, v0
	ds_bpermute_b32 v96, v100, v0
	v_and_b32_e32 v120, 0xffff0000, v148
	v_lshlrev_b32_e32 v121, 16, v149
	s_waitcnt lgkmcnt(0)
	v_add_f32_e32 v0, v0, v96
	ds_bpermute_b32 v96, v107, v0
	s_waitcnt lgkmcnt(0)
	v_add_f32_e32 v0, v0, v96
	v_mov_b32_e32 v96, 0x3727c5ac
	v_fmamk_f32 v0, v0, 0x3c000000, v96
	v_mul_f32_e32 v96, 0x4b800000, v0
	v_cmp_gt_f32_e32 vcc, s30, v0
	s_nop 1
	v_cndmask_b32_e32 v0, v0, v96, vcc
	v_lshlrev_b32_e32 v96, 16, v148
	v_mul_f32_e32 v100, 0xbfb8aa3b, v96
	v_rsq_f32_e32 v0, v0
	v_exp_f32_e32 v100, v100
	v_mul_f32_e32 v102, 0x45800000, v0
	v_add_f32_e32 v100, 1.0, v100
	v_cndmask_b32_e32 v0, v0, v102, vcc
	v_mul_f32_e32 v114, v114, v0
	s_waitcnt vmcnt(0) lgkmcnt(0)
	v_mul_f32_e32 v114, v119, v114
	v_mul_f32_e32 v112, v112, v0
	v_mul_f32_e32 v107, 0xbfb8aa3b, v120
	v_exp_f32_e32 v107, v107
	v_rcp_f32_e32 v102, v100
	s_nop 0
	v_fma_f32 v127, -v100, v102, 1.0
	v_fma_f32 v100, v127, v102, v102
	v_mul_f32_e32 v96, v100, v96
	v_cndmask_b32_e64 v96, v96, v100, s[40:41]
	v_add_f32_e32 v100, 1.0, v107
	v_div_scale_f32 v102, s[16:17], v100, v100, 1.0
	v_rcp_f32_e32 v107, v102
	v_mul_f32_e32 v123, v124, v0
	v_mul_f32_e32 v116, v116, v123
	v_mul_f32_e32 v96, v96, v116
	v_fma_f32 v116, -v102, v107, 1.0
	v_fmac_f32_e32 v107, v116, v107
	v_div_scale_f32 v116, vcc, 1.0, v100, 1.0
	v_mul_f32_e32 v123, v116, v107
	v_fma_f32 v124, -v102, v123, v116
	v_fmac_f32_e32 v123, v124, v107
	v_fma_f32 v102, -v102, v123, v116
	v_div_fmas_f32 v102, v102, v107, v123
	v_mul_f32_e32 v107, 0xbfb8aa3b, v121
	v_exp_f32_e32 v107, v107
	v_div_fixup_f32 v100, v102, v100, 1.0
	v_mul_f32_e32 v102, v100, v120
	v_cndmask_b32_e64 v100, v102, v100, s[40:41]
	v_add_f32_e32 v102, 1.0, v107
	v_mul_f32_e32 v120, v125, v0
	v_mul_f32_e32 v117, v117, v120
	v_mul_f32_e32 v100, v100, v117
	v_mul_f32_e32 v116, 0xbfb8aa3b, v122
	v_exp_f32_e32 v116, v116
	v_rcp_f32_e32 v107, v102
	s_nop 0
	v_fma_f32 v123, -v102, v107, 1.0
	v_fma_f32 v102, v123, v107, v107
	v_mul_f32_e32 v107, v102, v121
	v_cndmask_b32_e64 v102, v107, v102, s[40:41]
	v_add_f32_e32 v107, 1.0, v116
	v_mul_f32_e32 v120, v126, v0
	v_mul_f32_e32 v118, v118, v120
	v_mul_f32_e32 v102, v102, v118
	v_rcp_f32_e32 v116, v107
	s_nop 0
	v_fma_f32 v121, -v107, v116, 1.0
	v_fma_f32 v107, v121, v116, v116
	v_mul_f32_e32 v116, v107, v122
	v_cndmask_b32_e64 v107, v116, v107, s[40:41]
	v_mul_f32_e32 v107, v107, v114
	v_cvt_pk_bf16_f32 v116, v96, v100
	v_cvt_pk_bf16_f32 v117, v102, v107
	global_store_dwordx2 v[72:73], v[116:117], off
	v_bfe_u32 v116, v161, 4, 2
	v_lshlrev_b32_e32 v116, 4, v116
	v_add_u32_e32 v116, 0x25a80, v116
	ds_read_b128 v[116:119], v116 offset:64
	v_lshlrev_b32_e32 v96, 16, v146
	v_mul_f32_e32 v100, 0xbfb8aa3b, v96
	v_exp_f32_e32 v100, v100
	v_and_b32_e32 v114, 0xffff0000, v146
	v_lshlrev_b32_e32 v120, 16, v147
	v_and_b32_e32 v121, 0xffff0000, v147
	v_add_f32_e32 v100, 1.0, v100
	v_mul_f32_e32 v108, v108, v0
	v_mul_f32_e32 v90, v90, v0
	v_mul_f32_e32 v106, v106, v0
	v_mul_f32_e32 v107, 0xbfb8aa3b, v114
	v_exp_f32_e32 v107, v107
	v_rcp_f32_e32 v102, v100
	s_nop 0
	v_fma_f32 v123, -v100, v102, 1.0
	v_fma_f32 v100, v123, v102, v102
	v_mul_f32_e32 v96, v100, v96
	v_cndmask_b32_e64 v96, v96, v100, s[40:41]
	v_add_f32_e32 v100, 1.0, v107
	v_mul_f32_e32 v122, v145, v0
	v_mul_f32_e32 v92, v92, v0
	v_mul_f32_e32 v91, v91, v0
	v_mul_f32_e32 v101, v101, v0
	v_mul_f32_e32 v97, v97, v0
	v_mul_f32_e32 v93, v93, v0
	v_mul_f32_e32 v86, v86, v0
	v_mul_f32_e32 v87, v87, v0
	v_mul_f32_e32 v80, v80, v0
	v_mul_f32_e32 v81, v81, v0
	v_mul_f32_e32 v89, v89, v0
	v_mul_f32_e32 v83, v83, v0
	v_mul_f32_e32 v82, v82, v0
	v_mul_f32_e32 v79, v79, v0
	s_waitcnt lgkmcnt(0)
; __device__ __forceinline__ unsigned cvt_pk_bf16(float lo, float hi) { unsigned r; asm volatile("v_cvt_pk_bf16_f32 %0, %1, %2" : "=v"(r) : "v"(lo), "v"(hi)); return r; }
; __device__ __forceinline__ float bf_lo(unsigned w) { return __uint_as_float(w << 16); }
; __device__ __forceinline__ float bf_hi(unsigned w) { return __uint_as_float(w & 0xffff0000u); }
; __device__ __forceinline__ float sigmoidf_(float x) { return 1.0f / (1.0f + __expf(-x)); }
; __device__ void mix_sweep(const Params& P, LAS unsigned char* lds, int tok0, int pos0, int seqlen, int hd, int dir, bool state_only, bool final_pass,
;                           f32x4 (&Cacc)[9], float& m_state, float& aseg_sum, float lgam) {
;     ...
; #pragma unroll
;                 for (int nt = 0; nt < 8; ++nt) { const u32x2 gv = gvv[nt]; const f32x4 gw = *(const f32x4*)(gnw + 16 * nt + 4 * fg);
;                     float gt[4] = {bf_lo(gv.x), bf_hi(gv.x), bf_lo(gv.y), bf_hi(gv.y)}; float y[4];
; #pragma unroll
;                     for (int e = 0; e < 4; ++e) { const float sg = sigmoidf_(gt[e]); const float gate = is_m ? sg : gt[e] * sg; y[e] = (O[nt][e] - mu) * rs * gw[e] * gate; }
;                     u32x2 v; v.x = cvt_pk_bf16(y[0], y[1]); v.y = cvt_pk_bf16(y[2], y[3]); *(u32x2*)(mrow + 16 * nt) = v; }
	v_mul_f32_e32 v116, v116, v122
	v_mul_f32_e32 v96, v96, v116
	v_mul_f32_e32 v107, 0xbfb8aa3b, v120
	v_exp_f32_e32 v107, v107
	v_rcp_f32_e32 v102, v100
	s_nop 0
	v_fma_f32 v123, -v100, v102, 1.0
	v_fma_f32 v100, v123, v102, v102
	v_mul_f32_e32 v102, v100, v114
	v_cndmask_b32_e64 v100, v102, v100, s[40:41]
	v_add_f32_e32 v102, 1.0, v107
	v_mul_f32_e32 v116, v143, v0
	v_mul_f32_e32 v116, v117, v116
	v_mul_f32_e32 v100, v100, v116
	v_mul_f32_e32 v114, 0xbfb8aa3b, v121
	v_exp_f32_e32 v114, v114
	v_rcp_f32_e32 v107, v102
	s_nop 0
	v_fma_f32 v122, -v102, v107, 1.0
	v_fma_f32 v102, v122, v107, v107
	v_mul_f32_e32 v107, v102, v120
	v_cndmask_b32_e64 v102, v107, v102, s[40:41]
	v_add_f32_e32 v107, 1.0, v114
	v_mul_f32_e32 v117, v141, v0
	v_mul_f32_e32 v117, v118, v117
	v_mul_f32_e32 v102, v102, v117
	v_rcp_f32_e32 v114, v107
	s_nop 0
	v_fma_f32 v120, -v107, v114, 1.0
	v_fma_f32 v107, v120, v114, v114
	v_mul_f32_e32 v114, v107, v121
	v_cndmask_b32_e64 v107, v114, v107, s[40:41]
	v_mul_f32_e32 v114, v115, v0
	v_mul_f32_e32 v114, v119, v114
	v_mul_f32_e32 v107, v107, v114
	v_cvt_pk_bf16_f32 v114, v96, v100
	v_cvt_pk_bf16_f32 v115, v102, v107
	global_store_dwordx2 v[72:73], v[114:115], off offset:32
	v_bfe_u32 v114, v161, 4, 2
	v_lshlrev_b32_e32 v114, 4, v114
	v_add_u32_e32 v114, 0x25a80, v114
	ds_read_b128 v[114:117], v114 offset:128
	v_lshlrev_b32_e32 v96, 16, v110
	v_mul_f32_e32 v100, 0xbfb8aa3b, v96
	v_exp_f32_e32 v100, v100
	v_and_b32_e32 v110, 0xffff0000, v110
	v_lshlrev_b32_e32 v118, 16, v111
	v_and_b32_e32 v111, 0xffff0000, v111
	v_add_f32_e32 v100, 1.0, v100
	s_waitcnt lgkmcnt(0)
	v_mul_f32_e32 v112, v114, v112
	v_mul_f32_e32 v107, 0xbfb8aa3b, v110
	v_exp_f32_e32 v107, v107
	v_rcp_f32_e32 v102, v100
	s_nop 0
	v_fma_f32 v120, -v100, v102, 1.0
	v_fma_f32 v100, v120, v102, v102
	v_mul_f32_e32 v96, v100, v96
	v_cndmask_b32_e64 v96, v96, v100, s[40:41]
	v_add_f32_e32 v100, 1.0, v107
	v_mul_f32_e32 v96, v96, v112
	v_mul_f32_e32 v108, v116, v108
	v_mul_f32_e32 v107, 0xbfb8aa3b, v118
	v_exp_f32_e32 v107, v107
	v_rcp_f32_e32 v102, v100
	s_nop 0
	v_fma_f32 v114, -v100, v102, 1.0
	v_fma_f32 v100, v114, v102, v102
	v_mul_f32_e32 v102, v100, v110
	v_cndmask_b32_e64 v100, v102, v100, s[40:41]
	v_add_f32_e32 v102, 1.0, v107
	v_mul_f32_e32 v112, v113, v0
	v_mul_f32_e32 v112, v115, v112
	v_mul_f32_e32 v100, v100, v112
	v_mul_f32_e32 v110, 0xbfb8aa3b, v111
	v_exp_f32_e32 v110, v110
	v_rcp_f32_e32 v107, v102
	s_nop 0
	v_fma_f32 v114, -v102, v107, 1.0
	v_fma_f32 v102, v114, v107, v107
	v_mul_f32_e32 v107, v102, v118
	v_cndmask_b32_e64 v102, v107, v102, s[40:41]
	v_add_f32_e32 v107, 1.0, v110
	v_mul_f32_e32 v102, v102, v108
	v_rcp_f32_e32 v113, v107
	s_nop 0
	v_fma_f32 v114, -v107, v113, 1.0
	v_fma_f32 v107, v114, v113, v113
	v_mul_f32_e32 v108, v107, v111
	v_cndmask_b32_e64 v107, v108, v107, s[40:41]
	v_mul_f32_e32 v108, v109, v0
	v_mul_f32_e32 v108, v117, v108
	v_mul_f32_e32 v107, v107, v108
	v_cvt_pk_bf16_f32 v108, v96, v100
	v_cvt_pk_bf16_f32 v109, v102, v107
	global_store_dwordx2 v[72:73], v[108:109], off offset:64
	v_bfe_u32 v108, v161, 4, 2
	v_lshlrev_b32_e32 v108, 4, v108
	v_add_u32_e32 v108, 0x25a80, v108
	ds_read_b128 v[108:111], v108 offset:192
	v_lshlrev_b32_e32 v96, 16, v104
	v_mul_f32_e32 v100, 0xbfb8aa3b, v96
	v_exp_f32_e32 v100, v100
	v_and_b32_e32 v104, 0xffff0000, v104
	v_lshlrev_b32_e32 v112, 16, v105
	v_and_b32_e32 v105, 0xffff0000, v105
	v_add_f32_e32 v100, 1.0, v100
	s_waitcnt lgkmcnt(0)
	v_mul_f32_e32 v90, v108, v90
	v_mul_f32_e32 v107, 0xbfb8aa3b, v104
	v_exp_f32_e32 v107, v107
	v_rcp_f32_e32 v102, v100
	s_nop 0
	v_fma_f32 v114, -v100, v102, 1.0
	v_fma_f32 v100, v114, v102, v102
	v_mul_f32_e32 v96, v100, v96
	v_cndmask_b32_e64 v96, v96, v100, s[40:41]
	v_add_f32_e32 v100, 1.0, v107
	v_mul_f32_e32 v90, v96, v90
	v_mul_f32_e32 v106, v109, v106
	v_mul_f32_e32 v92, v110, v92
	v_mul_f32_e32 v102, 0xbfb8aa3b, v112
	v_exp_f32_e32 v102, v102
	v_rcp_f32_e32 v108, v100
	s_nop 0
	v_fma_f32 v113, -v100, v108, 1.0
	v_fma_f32 v96, v113, v108, v108
	v_mul_f32_e32 v100, v96, v104
	v_cndmask_b32_e64 v96, v100, v96, s[40:41]
	v_add_f32_e32 v100, 1.0, v102
	v_mul_f32_e32 v96, v96, v106
	v_mul_f32_e32 v91, v111, v91
	v_cvt_pk_bf16_f32 v90, v90, v96
	v_mul_f32_e32 v104, 0xbfb8aa3b, v105
	v_exp_f32_e32 v104, v104
	v_rcp_f32_e32 v102, v100
	s_nop 0
	v_fma_f32 v107, -v100, v102, 1.0
	v_fma_f32 v100, v107, v102, v102
	v_mul_f32_e32 v102, v100, v112
	v_cndmask_b32_e64 v100, v102, v100, s[40:41]
	v_add_f32_e32 v102, 1.0, v104
	v_mul_f32_e32 v92, v100, v92
	v_rcp_f32_e32 v107, v102
	s_nop 0
	v_fma_f32 v108, -v102, v107, 1.0
	v_fma_f32 v100, v108, v107, v107
	v_mul_f32_e32 v102, v100, v105
	v_cndmask_b32_e64 v100, v102, v100, s[40:41]
	v_mul_f32_e32 v91, v100, v91
	v_cvt_pk_bf16_f32 v91, v92, v91
	global_store_dwordx2 v[72:73], v[90:91], off offset:96
	v_bfe_u32 v104, v161, 4, 2
	v_lshlrev_b32_e32 v104, 4, v104
	v_add_u32_e32 v104, 0x25a80, v104
	ds_read_b128 v[104:107], v104 offset:256
	v_lshlrev_b32_e32 v90, 16, v94
	v_mul_f32_e32 v91, 0xbfb8aa3b, v90
	v_exp_f32_e32 v91, v91
	v_and_b32_e32 v94, 0xffff0000, v94
	v_lshlrev_b32_e32 v100, 16, v95
	v_and_b32_e32 v95, 0xffff0000, v95
	v_add_f32_e32 v91, 1.0, v91
	s_waitcnt lgkmcnt(0)
; __device__ __forceinline__ unsigned cvt_pk_bf16(float lo, float hi) { unsigned r; asm volatile("v_cvt_pk_bf16_f32 %0, %1, %2" : "=v"(r) : "v"(lo), "v"(hi)); return r; }
; __device__ __forceinline__ float bf_lo(unsigned w) { return __uint_as_float(w << 16); }
; __device__ __forceinline__ float bf_hi(unsigned w) { return __uint_as_float(w & 0xffff0000u); }
; __device__ __forceinline__ float sigmoidf_(float x) { return 1.0f / (1.0f + __expf(-x)); }
; __device__ void mix_sweep(const Params& P, LAS unsigned char* lds, int tok0, int pos0, int seqlen, int hd, int dir, bool state_only, bool final_pass,
;                           f32x4 (&Cacc)[9], float& m_state, float& aseg_sum, float lgam) {
;     ...
; #pragma unroll
;                 for (int nt = 0; nt < 8; ++nt) { const u32x2 gv = gvv[nt]; const f32x4 gw = *(const f32x4*)(gnw + 16 * nt + 4 * fg);
;                     float gt[4] = {bf_lo(gv.x), bf_hi(gv.x), bf_lo(gv.y), bf_hi(gv.y)}; float y[4];
; #pragma unroll
;                     for (int e = 0; e < 4; ++e) { const float sg = sigmoidf_(gt[e]); const float gate = is_m ? sg : gt[e] * sg; y[e] = (O[nt][e] - mu) * rs * gw[e] * gate; }
;                     u32x2 v; v.x = cvt_pk_bf16(y[0], y[1]); v.y = cvt_pk_bf16(y[2], y[3]); *(u32x2*)(mrow + 16 * nt) = v; }
	v_mul_f32_e32 v101, v105, v101
	v_mul_f32_e32 v96, 0xbfb8aa3b, v94
	v_exp_f32_e32 v96, v96
	v_rcp_f32_e32 v92, v91
	s_nop 0
	v_fma_f32 v108, -v91, v92, 1.0
	v_fma_f32 v91, v108, v92, v92
	v_mul_f32_e32 v90, v91, v90
	v_cndmask_b32_e64 v90, v90, v91, s[40:41]
	v_add_f32_e32 v91, 1.0, v96
	v_div_scale_f32 v92, s[16:17], v91, v91, 1.0
	v_rcp_f32_e32 v96, v92
	v_mul_f32_e32 v102, v103, v0
	v_mul_f32_e32 v102, v104, v102
	v_mul_f32_e32 v90, v90, v102
	v_fma_f32 v102, -v92, v96, 1.0
	v_fmac_f32_e32 v96, v102, v96
	v_div_scale_f32 v102, vcc, 1.0, v91, 1.0
	v_mul_f32_e32 v103, v102, v96
	v_fma_f32 v104, -v92, v103, v102
	v_fmac_f32_e32 v103, v104, v96
	v_fma_f32 v92, -v92, v103, v102
	v_div_fmas_f32 v92, v92, v96, v103
	v_mul_f32_e32 v96, 0xbfb8aa3b, v100
	v_exp_f32_e32 v96, v96
	v_div_fixup_f32 v91, v92, v91, 1.0
	v_mul_f32_e32 v92, v91, v94
	v_cndmask_b32_e64 v91, v92, v91, s[40:41]
	v_add_f32_e32 v92, 1.0, v96
	v_mul_f32_e32 v91, v91, v101
	v_mul_f32_e32 v97, v106, v97
	v_mul_f32_e32 v93, v107, v93
	v_mul_f32_e32 v96, 0xbfb8aa3b, v95
	v_exp_f32_e32 v96, v96
	v_rcp_f32_e32 v94, v92
	s_nop 0
	v_fma_f32 v102, -v92, v94, 1.0
	v_fma_f32 v92, v102, v94, v94
	v_mul_f32_e32 v94, v92, v100
	v_cndmask_b32_e64 v92, v94, v92, s[40:41]
	v_add_f32_e32 v94, 1.0, v96
	v_mul_f32_e32 v92, v92, v97
	v_cvt_pk_bf16_f32 v90, v90, v91
	v_rcp_f32_e32 v96, v94
	s_nop 0
	v_fma_f32 v101, -v94, v96, 1.0
	v_fma_f32 v94, v101, v96, v96
	v_mul_f32_e32 v95, v94, v95
	v_cndmask_b32_e64 v94, v95, v94, s[40:41]
	v_mul_f32_e32 v93, v94, v93
	v_cvt_pk_bf16_f32 v91, v92, v93
	global_store_dwordx2 v[72:73], v[90:91], off offset:128
	v_bfe_u32 v90, v161, 4, 2
	v_lshlrev_b32_e32 v90, 4, v90
	v_add_u32_e32 v90, 0x25a80, v90
	ds_read_b128 v[90:93], v90 offset:320
	v_lshlrev_b32_e32 v94, 16, v84
	v_mul_f32_e32 v95, 0xbfb8aa3b, v94
	v_exp_f32_e32 v95, v95
	v_and_b32_e32 v84, 0xffff0000, v84
	v_lshlrev_b32_e32 v100, 16, v85
	v_and_b32_e32 v85, 0xffff0000, v85
	v_add_f32_e32 v95, 1.0, v95
	s_waitcnt lgkmcnt(0)
	v_mul_f32_e32 v86, v90, v86
	v_mul_f32_e32 v97, 0xbfb8aa3b, v84
	v_exp_f32_e32 v97, v97
	v_rcp_f32_e32 v96, v95
	s_nop 0
	v_fma_f32 v102, -v95, v96, 1.0
	v_fma_f32 v95, v102, v96, v96
	v_mul_f32_e32 v94, v95, v94
	v_cndmask_b32_e64 v94, v94, v95, s[40:41]
	v_add_f32_e32 v95, 1.0, v97
	v_mul_f32_e32 v86, v94, v86
	v_mul_f32_e32 v87, v91, v87
	v_mul_f32_e32 v80, v92, v80
	v_mul_f32_e32 v94, 0xbfb8aa3b, v100
	v_exp_f32_e32 v94, v94
	v_rcp_f32_e32 v101, v95
	s_nop 0
	v_fma_f32 v97, -v95, v101, 1.0
	v_fma_f32 v90, v97, v101, v101
	v_mul_f32_e32 v84, v90, v84
	v_cndmask_b32_e64 v84, v84, v90, s[40:41]
	v_add_f32_e32 v90, 1.0, v94
	v_mul_f32_e32 v84, v84, v87
	v_mul_f32_e32 v81, v93, v81
	v_mul_f32_e32 v91, 0xbfb8aa3b, v85
	v_exp_f32_e32 v91, v91
	v_rcp_f32_e32 v96, v90
	s_nop 0
	v_fma_f32 v95, -v90, v96, 1.0
	v_fma_f32 v87, v95, v96, v96
	v_mul_f32_e32 v90, v87, v100
	v_cndmask_b32_e64 v87, v90, v87, s[40:41]
	v_add_f32_e32 v90, 1.0, v91
	v_mul_f32_e32 v87, v87, v80
	v_rcp_f32_e32 v92, v90
	s_nop 0
	v_fma_f32 v95, -v90, v92, 1.0
	v_fma_f32 v80, v95, v92, v92
	v_mul_f32_e32 v85, v80, v85
	v_cndmask_b32_e64 v80, v85, v80, s[40:41]
	v_mul_f32_e32 v81, v80, v81
	v_cvt_pk_bf16_f32 v80, v86, v84
	v_cvt_pk_bf16_f32 v81, v87, v81
	global_store_dwordx2 v[72:73], v[80:81], off offset:160
	v_bfe_u32 v84, v161, 4, 2
	v_lshlrev_b32_e32 v84, 4, v84
	v_add_u32_e32 v84, 0x25a80, v84
	ds_read_b128 v[84:87], v84 offset:384
	v_lshlrev_b32_e32 v80, 16, v76
	v_mul_f32_e32 v81, 0xbfb8aa3b, v80
	v_exp_f32_e32 v81, v81
	v_and_b32_e32 v76, 0xffff0000, v76
	v_lshlrev_b32_e32 v92, 16, v77
	v_and_b32_e32 v77, 0xffff0000, v77
	v_add_f32_e32 v81, 1.0, v81
	s_waitcnt lgkmcnt(0)
	v_mul_f32_e32 v86, v86, v89
	v_mul_f32_e32 v91, 0xbfb8aa3b, v76
	v_exp_f32_e32 v91, v91
	v_rcp_f32_e32 v90, v81
	s_nop 0
	v_fma_f32 v94, -v81, v90, 1.0
	v_fma_f32 v81, v94, v90, v90
	v_mul_f32_e32 v80, v81, v80
	v_cndmask_b32_e64 v80, v80, v81, s[40:41]
	v_add_f32_e32 v81, 1.0, v91
	v_mul_f32_e32 v93, v98, v0
	v_mul_f32_e32 v84, v84, v93
	v_mul_f32_e32 v80, v80, v84
	v_mul_f32_e32 v90, 0xbfb8aa3b, v92
	v_exp_f32_e32 v90, v90
	v_rcp_f32_e32 v94, v81
	s_nop 0
	v_fma_f32 v91, -v81, v94, 1.0
	v_fma_f32 v81, v91, v94, v94
	v_mul_f32_e32 v76, v81, v76
	v_cndmask_b32_e64 v76, v76, v81, s[40:41]
	v_add_f32_e32 v81, 1.0, v90
	v_mul_f32_e32 v91, v99, v0
	v_mul_f32_e32 v85, v85, v91
	v_mul_f32_e32 v76, v76, v85
	v_mul_f32_e32 v85, 0xbfb8aa3b, v77
	v_exp_f32_e32 v85, v85
	v_rcp_f32_e32 v84, v81
	s_nop 0
	v_fma_f32 v93, -v81, v84, 1.0
	v_fma_f32 v81, v93, v84, v84
	v_mul_f32_e32 v84, v81, v92
	v_cndmask_b32_e64 v81, v84, v81, s[40:41]
	v_add_f32_e32 v84, 1.0, v85
	v_mul_f32_e32 v81, v81, v86
	v_cvt_pk_bf16_f32 v76, v80, v76
	v_rcp_f32_e32 v85, v84
	s_nop 0
	v_fma_f32 v89, -v84, v85, 1.0
	v_fma_f32 v84, v89, v85, v85
	v_mul_f32_e32 v77, v84, v77
	v_cndmask_b32_e64 v77, v77, v84, s[40:41]
	v_mul_f32_e32 v84, v88, v0
	v_mul_f32_e32 v84, v87, v84
	v_mul_f32_e32 v77, v77, v84
	v_cvt_pk_bf16_f32 v77, v81, v77
	global_store_dwordx2 v[72:73], v[76:77], off offset:192
	v_bfe_u32 v84, v161, 4, 2
	v_lshlrev_b32_e32 v84, 4, v84
	v_add_u32_e32 v84, 0x25a80, v84
	ds_read_b128 v[84:87], v84 offset:448
	v_lshlrev_b32_e32 v76, 16, v74
	v_mul_f32_e32 v77, 0xbfb8aa3b, v76
	v_exp_f32_e32 v77, v77
	v_and_b32_e32 v74, 0xffff0000, v74
	v_lshlrev_b32_e32 v88, 16, v75
	v_and_b32_e32 v75, 0xffff0000, v75
	v_add_f32_e32 v77, 1.0, v77
	v_mul_f32_e32 v0, v78, v0
	v_mul_f32_e32 v81, 0xbfb8aa3b, v74
	v_exp_f32_e32 v81, v81
	v_rcp_f32_e32 v80, v77
	s_nop 0
	v_fma_f32 v90, -v77, v80, 1.0
	v_fma_f32 v77, v90, v80, v80
	v_mul_f32_e32 v76, v77, v76
	v_cndmask_b32_e64 v76, v76, v77, s[40:41]
	v_add_f32_e32 v77, 1.0, v81
	s_waitcnt lgkmcnt(0)
	v_mul_f32_e32 v83, v84, v83
	v_mul_f32_e32 v76, v76, v83
	v_mul_f32_e32 v81, 0xbfb8aa3b, v88
	v_exp_f32_e32 v81, v81
	v_rcp_f32_e32 v80, v77
	s_nop 0
	v_fma_f32 v89, -v77, v80, 1.0
	v_fma_f32 v77, v89, v80, v80
	v_mul_f32_e32 v74, v77, v74
	v_cndmask_b32_e64 v74, v74, v77, s[40:41]
	v_add_f32_e32 v77, 1.0, v81
	v_mul_f32_e32 v82, v85, v82
	v_mul_f32_e32 v74, v74, v82
	v_mul_f32_e32 v79, v86, v79
	v_mul_f32_e32 v81, 0xbfb8aa3b, v75
	v_exp_f32_e32 v81, v81
	v_rcp_f32_e32 v80, v77
	s_nop 0
	v_fma_f32 v83, -v77, v80, 1.0
	v_fma_f32 v77, v83, v80, v80
	v_mul_f32_e32 v80, v77, v88
	v_cndmask_b32_e64 v77, v80, v77, s[40:41]
	v_add_f32_e32 v80, 1.0, v81
	v_mul_f32_e32 v77, v77, v79
	v_mul_f32_e32 v0, v87, v0
	v_cvt_pk_bf16_f32 v74, v76, v74
	v_rcp_f32_e32 v83, v80
	s_nop 0
	v_fma_f32 v84, -v80, v83, 1.0
	v_fma_f32 v79, v84, v83, v83
	v_mul_f32_e32 v75, v79, v75
	v_cndmask_b32_e64 v75, v75, v79, s[40:41]
	v_mul_f32_e32 v0, v75, v0
	v_cvt_pk_bf16_f32 v75, v77, v0
	global_store_dwordx2 v[72:73], v[74:75], off offset:224
	s_branch .LBB0_97
